# GEMM K-loops: first vmcnt wait of a unit's first K iteration skipped (retires nothing; avoids waiting for epilogue stores)
# baseline (speedup 1.0000x reference)
.LBB5_248:
	ds_read_b128 v[148:151], v175
	ds_read_b128 v[152:155], v175 offset:1024
	ds_read_b128 v[156:159], v175 offset:2048
	ds_read_b128 v[160:163], v175 offset:3072
	ds_read_b128 v[164:167], v176
	ds_read_b128 v[168:171], v176 offset:1024
	ds_read_b128 v[178:181], v176 offset:2048
	ds_read_b128 v[182:185], v176 offset:3072
	s_add_u32 s27, s42, 0xfffc0080
	s_addc_u32 s30, s43, -1
	s_cmp_eq_u32 s25, 12
	s_cselect_b32 s47, s3, s30
	s_cselect_b32 s46, s5, s27
	s_cselect_b32 s45, s7, s24
	s_cselect_b32 s44, s12, s23
	v_lshl_add_u64 v[218:219], s[42:43], 0, v[140:141]
	s_add_i32 m0, s51, 0xc000
	ds_read_b128 v[186:189], v177
	ds_read_b128 v[190:193], v177 offset:1024
	ds_read_b128 v[194:197], v177 offset:2048
	ds_read_b128 v[198:201], v177 offset:3072
	ds_read_b128 v[202:205], v177 offset:4096
	ds_read_b128 v[206:209], v177 offset:5120
	ds_read_b128 v[210:213], v177 offset:6144
	ds_read_b128 v[214:217], v177 offset:7168
	global_load_lds_dwordx4 v[218:219], off
	v_lshl_add_u64 v[218:219], s[42:43], 0, v[142:143]
	s_add_i32 m0, s51, 0xe000
	s_nop 0
	global_load_lds_dwordx4 v[218:219], off
	s_cmp_eq_u32 s25, -2
	s_cbranch_scc1 .Lskw_P1
	s_waitcnt vmcnt(8)
.Lskw_P1:
	s_waitcnt lgkmcnt(0)
	s_barrier
	s_setprio 1
	s_waitcnt lgkmcnt(0)
	v_mfma_f32_16x16x32_bf16 v[124:127], v[148:151], v[186:189], v[124:127]
	v_mfma_f32_16x16x32_bf16 v[120:123], v[156:159], v[186:189], v[120:123]
	v_mfma_f32_16x16x32_bf16 v[108:111], v[148:151], v[194:197], v[108:111]
	v_mfma_f32_16x16x32_bf16 v[104:107], v[156:159], v[194:197], v[104:107]
	v_mfma_f32_16x16x32_bf16 v[92:95], v[148:151], v[202:205], v[92:95]
	v_mfma_f32_16x16x32_bf16 v[88:91], v[156:159], v[202:205], v[88:91]
	v_mfma_f32_16x16x32_bf16 v[76:79], v[148:151], v[210:213], v[76:79]
	v_mfma_f32_16x16x32_bf16 v[72:75], v[156:159], v[210:213], v[72:75]
	v_mfma_f32_16x16x32_bf16 v[124:127], v[152:155], v[190:193], v[124:127]
	v_mfma_f32_16x16x32_bf16 v[120:123], v[160:163], v[190:193], v[120:123]
	v_mfma_f32_16x16x32_bf16 v[108:111], v[152:155], v[198:201], v[108:111]
	v_mfma_f32_16x16x32_bf16 v[104:107], v[160:163], v[198:201], v[104:107]
	v_mfma_f32_16x16x32_bf16 v[92:95], v[152:155], v[206:209], v[92:95]
	v_mfma_f32_16x16x32_bf16 v[88:91], v[160:163], v[206:209], v[88:91]
	v_mfma_f32_16x16x32_bf16 v[76:79], v[152:155], v[214:217], v[76:79]
	v_mfma_f32_16x16x32_bf16 v[72:75], v[160:163], v[214:217], v[72:75]
	s_setprio 0
	s_setprio 1
	v_mfma_f32_16x16x32_bf16 v[116:119], v[164:167], v[186:189], v[116:119]
	v_mfma_f32_16x16x32_bf16 v[112:115], v[178:181], v[186:189], v[112:115]
	v_mfma_f32_16x16x32_bf16 v[100:103], v[164:167], v[194:197], v[100:103]
	v_mfma_f32_16x16x32_bf16 v[96:99], v[178:181], v[194:197], v[96:99]
	v_mfma_f32_16x16x32_bf16 v[84:87], v[164:167], v[202:205], v[84:87]
	v_mfma_f32_16x16x32_bf16 v[80:83], v[178:181], v[202:205], v[80:83]
	v_mfma_f32_16x16x32_bf16 v[68:71], v[164:167], v[210:213], v[68:71]
	v_mfma_f32_16x16x32_bf16 v[64:67], v[178:181], v[210:213], v[64:67]
	v_mfma_f32_16x16x32_bf16 v[116:119], v[168:171], v[190:193], v[116:119]
	v_mfma_f32_16x16x32_bf16 v[112:115], v[182:185], v[190:193], v[112:115]
	v_mfma_f32_16x16x32_bf16 v[100:103], v[168:171], v[198:201], v[100:103]
	v_mfma_f32_16x16x32_bf16 v[96:99], v[182:185], v[198:201], v[96:99]
	v_mfma_f32_16x16x32_bf16 v[84:87], v[168:171], v[206:209], v[84:87]
	v_mfma_f32_16x16x32_bf16 v[80:83], v[182:185], v[206:209], v[80:83]
	v_mfma_f32_16x16x32_bf16 v[68:71], v[168:171], v[214:217], v[68:71]
	v_mfma_f32_16x16x32_bf16 v[64:67], v[182:185], v[214:217], v[64:67]
	s_setprio 0
	s_barrier
	s_add_i32 s27, s64, s50
	v_lshl_add_u64 v[218:219], s[44:45], 0, v[130:131]
	s_mov_b32 m0, s27
	ds_read_b128 v[186:189], v177 offset:16384
	ds_read_b128 v[190:193], v177 offset:17408
	ds_read_b128 v[194:197], v177 offset:18432
	ds_read_b128 v[198:201], v177 offset:19456
	ds_read_b128 v[202:205], v177 offset:20480
	ds_read_b128 v[206:209], v177 offset:21504
	ds_read_b128 v[210:213], v177 offset:22528
	ds_read_b128 v[214:217], v177 offset:23552
	global_load_lds_dwordx4 v[218:219], off
	s_add_i32 m0, s27, 0x2000
	s_add_u32 s34, s44, 0x40000
	v_lshl_add_u64 v[220:221], s[44:45], 0, v[134:135]
	s_addc_u32 s35, s45, 0
	s_add_i32 s27, s65, s50
	global_load_lds_dwordx4 v[220:221], off
	v_lshl_add_u64 v[222:223], s[34:35], 0, v[130:131]
	s_mov_b32 m0, s27
	v_lshl_add_u64 v[224:225], s[46:47], 0, v[132:133]
	global_load_lds_dwordx4 v[222:223], off
	v_lshl_add_u64 v[222:223], s[34:35], 0, v[134:135]
	s_add_i32 m0, s27, 0x2000
	s_nop 0
	global_load_lds_dwordx4 v[222:223], off
	v_lshl_add_u64 v[222:223], s[46:47], 0, v[128:129]
	s_mov_b32 m0, s51
	s_nop 0
	global_load_lds_dwordx4 v[222:223], off
	s_mov_b32 m0, s52
	s_nop 0
	global_load_lds_dwordx4 v[224:225], off
	s_waitcnt vmcnt(8)
	s_waitcnt lgkmcnt(0)
	s_barrier
	s_setprio 1
	s_waitcnt lgkmcnt(0)
	v_mfma_f32_16x16x32_bf16 v[60:63], v[148:151], v[186:189], v[60:63]
	v_mfma_f32_16x16x32_bf16 v[56:59], v[156:159], v[186:189], v[56:59]
	v_mfma_f32_16x16x32_bf16 v[44:47], v[148:151], v[194:197], v[44:47]
	v_mfma_f32_16x16x32_bf16 v[40:43], v[156:159], v[194:197], v[40:43]
	v_mfma_f32_16x16x32_bf16 v[28:31], v[148:151], v[202:205], v[28:31]
	v_mfma_f32_16x16x32_bf16 v[24:27], v[156:159], v[202:205], v[24:27]
	v_mfma_f32_16x16x32_bf16 v[12:15], v[148:151], v[210:213], v[12:15]
	v_mfma_f32_16x16x32_bf16 v[8:11], v[156:159], v[210:213], v[8:11]
	v_mfma_f32_16x16x32_bf16 v[60:63], v[152:155], v[190:193], v[60:63]
	v_mfma_f32_16x16x32_bf16 v[56:59], v[160:163], v[190:193], v[56:59]
	v_mfma_f32_16x16x32_bf16 v[44:47], v[152:155], v[198:201], v[44:47]
	v_mfma_f32_16x16x32_bf16 v[40:43], v[160:163], v[198:201], v[40:43]
	v_mfma_f32_16x16x32_bf16 v[28:31], v[152:155], v[206:209], v[28:31]
	v_mfma_f32_16x16x32_bf16 v[24:27], v[160:163], v[206:209], v[24:27]
	v_mfma_f32_16x16x32_bf16 v[12:15], v[152:155], v[214:217], v[12:15]
	v_mfma_f32_16x16x32_bf16 v[8:11], v[160:163], v[214:217], v[8:11]
	s_setprio 0
	s_setprio 1
	v_mfma_f32_16x16x32_bf16 v[52:55], v[164:167], v[186:189], v[52:55]
	v_mfma_f32_16x16x32_bf16 v[48:51], v[178:181], v[186:189], v[48:51]
	v_mfma_f32_16x16x32_bf16 v[36:39], v[164:167], v[194:197], v[36:39]
	v_mfma_f32_16x16x32_bf16 v[32:35], v[178:181], v[194:197], v[32:35]
	v_mfma_f32_16x16x32_bf16 v[20:23], v[164:167], v[202:205], v[20:23]
	v_mfma_f32_16x16x32_bf16 v[16:19], v[178:181], v[202:205], v[16:19]
	v_mfma_f32_16x16x32_bf16 v[4:7], v[164:167], v[210:213], v[4:7]
	v_mfma_f32_16x16x32_bf16 v[0:3], v[178:181], v[210:213], v[0:3]
	v_mfma_f32_16x16x32_bf16 v[52:55], v[168:171], v[190:193], v[52:55]
	v_mfma_f32_16x16x32_bf16 v[48:51], v[182:185], v[190:193], v[48:51]
	v_mfma_f32_16x16x32_bf16 v[36:39], v[168:171], v[198:201], v[36:39]
	v_mfma_f32_16x16x32_bf16 v[32:35], v[182:185], v[198:201], v[32:35]
	v_mfma_f32_16x16x32_bf16 v[20:23], v[168:171], v[206:209], v[20:23]
	v_mfma_f32_16x16x32_bf16 v[16:19], v[182:185], v[206:209], v[16:19]
	v_mfma_f32_16x16x32_bf16 v[4:7], v[168:171], v[214:217], v[4:7]
	v_mfma_f32_16x16x32_bf16 v[0:3], v[182:185], v[214:217], v[0:3]
	s_setprio 0
	s_barrier
	s_add_i32 s27, 0, 0x18000
	v_add_u32_e32 v136, s27, v173
	s_add_i32 s30, 0, 0x1c000
	ds_read_b128 v[148:151], v136
	ds_read_b128 v[152:155], v136 offset:1024
	ds_read_b128 v[156:159], v136 offset:2048
	ds_read_b128 v[160:163], v136 offset:3072
	v_add_u32_e32 v136, s30, v173
	ds_read_b128 v[164:167], v136
	ds_read_b128 v[168:171], v136 offset:1024
	ds_read_b128 v[178:181], v136 offset:2048
	ds_read_b128 v[182:185], v136 offset:3072
	s_add_u32 s34, s46, 0x40000
	s_addc_u32 s35, s47, 0
	s_mov_b32 m0, s53
	v_lshl_add_u64 v[226:227], s[34:35], 0, v[128:129]
	ds_read_b128 v[186:189], v177 offset:32768
	ds_read_b128 v[190:193], v177 offset:33792
	ds_read_b128 v[194:197], v177 offset:34816
	ds_read_b128 v[198:201], v177 offset:35840
	ds_read_b128 v[202:205], v177 offset:36864
	ds_read_b128 v[206:209], v177 offset:37888
	ds_read_b128 v[210:213], v177 offset:38912
	ds_read_b128 v[214:217], v177 offset:39936
	global_load_lds_dwordx4 v[226:227], off
	v_lshl_add_u64 v[226:227], s[34:35], 0, v[132:133]
	s_mov_b32 m0, s54
	s_nop 0
	global_load_lds_dwordx4 v[226:227], off
	s_waitcnt vmcnt(8)
	s_waitcnt lgkmcnt(0)
	s_barrier
	s_setprio 1
	s_waitcnt lgkmcnt(0)
	v_mfma_f32_16x16x32_bf16 v[124:127], v[148:151], v[186:189], v[124:127]
	v_mfma_f32_16x16x32_bf16 v[120:123], v[156:159], v[186:189], v[120:123]
	v_mfma_f32_16x16x32_bf16 v[108:111], v[148:151], v[194:197], v[108:111]
	v_mfma_f32_16x16x32_bf16 v[104:107], v[156:159], v[194:197], v[104:107]
	v_mfma_f32_16x16x32_bf16 v[92:95], v[148:151], v[202:205], v[92:95]
	v_mfma_f32_16x16x32_bf16 v[88:91], v[156:159], v[202:205], v[88:91]
	v_mfma_f32_16x16x32_bf16 v[76:79], v[148:151], v[210:213], v[76:79]
	v_mfma_f32_16x16x32_bf16 v[72:75], v[156:159], v[210:213], v[72:75]
	v_mfma_f32_16x16x32_bf16 v[124:127], v[152:155], v[190:193], v[124:127]
	v_mfma_f32_16x16x32_bf16 v[120:123], v[160:163], v[190:193], v[120:123]
	v_mfma_f32_16x16x32_bf16 v[108:111], v[152:155], v[198:201], v[108:111]
	v_mfma_f32_16x16x32_bf16 v[104:107], v[160:163], v[198:201], v[104:107]
	v_mfma_f32_16x16x32_bf16 v[92:95], v[152:155], v[206:209], v[92:95]
	v_mfma_f32_16x16x32_bf16 v[88:91], v[160:163], v[206:209], v[88:91]
	v_mfma_f32_16x16x32_bf16 v[76:79], v[152:155], v[214:217], v[76:79]
	v_mfma_f32_16x16x32_bf16 v[72:75], v[160:163], v[214:217], v[72:75]
	s_setprio 0
	s_setprio 1
	v_mfma_f32_16x16x32_bf16 v[116:119], v[164:167], v[186:189], v[116:119]
	v_mfma_f32_16x16x32_bf16 v[112:115], v[178:181], v[186:189], v[112:115]
	v_mfma_f32_16x16x32_bf16 v[100:103], v[164:167], v[194:197], v[100:103]
	v_mfma_f32_16x16x32_bf16 v[96:99], v[178:181], v[194:197], v[96:99]
	v_mfma_f32_16x16x32_bf16 v[84:87], v[164:167], v[202:205], v[84:87]
	v_mfma_f32_16x16x32_bf16 v[80:83], v[178:181], v[202:205], v[80:83]
	v_mfma_f32_16x16x32_bf16 v[68:71], v[164:167], v[210:213], v[68:71]
	v_mfma_f32_16x16x32_bf16 v[64:67], v[178:181], v[210:213], v[64:67]
	v_mfma_f32_16x16x32_bf16 v[116:119], v[168:171], v[190:193], v[116:119]
	v_mfma_f32_16x16x32_bf16 v[112:115], v[182:185], v[190:193], v[112:115]
	v_mfma_f32_16x16x32_bf16 v[100:103], v[168:171], v[198:201], v[100:103]
	v_mfma_f32_16x16x32_bf16 v[96:99], v[182:185], v[198:201], v[96:99]
	v_mfma_f32_16x16x32_bf16 v[84:87], v[168:171], v[206:209], v[84:87]
	v_mfma_f32_16x16x32_bf16 v[80:83], v[182:185], v[206:209], v[80:83]
	v_mfma_f32_16x16x32_bf16 v[68:71], v[168:171], v[214:217], v[68:71]
	v_mfma_f32_16x16x32_bf16 v[64:67], v[182:185], v[214:217], v[64:67]
	s_setprio 0
	s_barrier
	s_add_i32 s27, s27, s50
	v_lshl_add_u64 v[218:219], v[218:219], 0, s[20:21]
	s_mov_b32 m0, s27
	ds_read_b128 v[186:189], v177 offset:49152
	ds_read_b128 v[190:193], v177 offset:50176
	ds_read_b128 v[194:197], v177 offset:51200
	ds_read_b128 v[198:201], v177 offset:52224
	ds_read_b128 v[202:205], v177 offset:53248
	ds_read_b128 v[206:209], v177 offset:54272
	ds_read_b128 v[210:213], v177 offset:55296
	ds_read_b128 v[214:217], v177 offset:56320
	global_load_lds_dwordx4 v[218:219], off
	s_add_i32 m0, s27, 0x2000
	s_add_u32 s34, s44, 0x40080
	v_lshl_add_u64 v[218:219], v[220:221], 0, s[20:21]
	s_addc_u32 s35, s45, 0
	s_add_i32 s27, s30, s50
	global_load_lds_dwordx4 v[218:219], off
	v_lshl_add_u64 v[218:219], s[34:35], 0, v[130:131]
	s_mov_b32 m0, s27
	s_nop 0
	global_load_lds_dwordx4 v[218:219], off
	v_lshl_add_u64 v[218:219], s[34:35], 0, v[134:135]
	s_add_i32 m0, s27, 0x2000
	s_nop 0
	global_load_lds_dwordx4 v[218:219], off
	v_lshl_add_u64 v[218:219], v[222:223], 0, s[20:21]
	s_mov_b32 m0, s62
	s_nop 0
	global_load_lds_dwordx4 v[218:219], off
	v_lshl_add_u64 v[218:219], v[224:225], 0, s[20:21]
	s_mov_b32 m0, s63
	s_nop 0
	global_load_lds_dwordx4 v[218:219], off
	s_waitcnt vmcnt(8)
	s_waitcnt lgkmcnt(0)
	s_barrier
	s_setprio 1
	s_waitcnt lgkmcnt(0)
	v_mfma_f32_16x16x32_bf16 v[60:63], v[148:151], v[186:189], v[60:63]
	v_mfma_f32_16x16x32_bf16 v[56:59], v[156:159], v[186:189], v[56:59]
	v_mfma_f32_16x16x32_bf16 v[44:47], v[148:151], v[194:197], v[44:47]
	v_mfma_f32_16x16x32_bf16 v[40:43], v[156:159], v[194:197], v[40:43]
	v_mfma_f32_16x16x32_bf16 v[28:31], v[148:151], v[202:205], v[28:31]
	v_mfma_f32_16x16x32_bf16 v[24:27], v[156:159], v[202:205], v[24:27]
	v_mfma_f32_16x16x32_bf16 v[12:15], v[148:151], v[210:213], v[12:15]
	v_mfma_f32_16x16x32_bf16 v[8:11], v[156:159], v[210:213], v[8:11]
	v_mfma_f32_16x16x32_bf16 v[60:63], v[152:155], v[190:193], v[60:63]
	v_mfma_f32_16x16x32_bf16 v[56:59], v[160:163], v[190:193], v[56:59]
	v_mfma_f32_16x16x32_bf16 v[44:47], v[152:155], v[198:201], v[44:47]
	v_mfma_f32_16x16x32_bf16 v[40:43], v[160:163], v[198:201], v[40:43]
	v_mfma_f32_16x16x32_bf16 v[28:31], v[152:155], v[206:209], v[28:31]
	v_mfma_f32_16x16x32_bf16 v[24:27], v[160:163], v[206:209], v[24:27]
	v_mfma_f32_16x16x32_bf16 v[12:15], v[152:155], v[214:217], v[12:15]
	v_mfma_f32_16x16x32_bf16 v[8:11], v[160:163], v[214:217], v[8:11]
	s_setprio 0
	s_setprio 1
	v_mfma_f32_16x16x32_bf16 v[52:55], v[164:167], v[186:189], v[52:55]
	v_mfma_f32_16x16x32_bf16 v[48:51], v[178:181], v[186:189], v[48:51]
	v_mfma_f32_16x16x32_bf16 v[36:39], v[164:167], v[194:197], v[36:39]
	v_mfma_f32_16x16x32_bf16 v[32:35], v[178:181], v[194:197], v[32:35]
	v_mfma_f32_16x16x32_bf16 v[20:23], v[164:167], v[202:205], v[20:23]
	v_mfma_f32_16x16x32_bf16 v[16:19], v[178:181], v[202:205], v[16:19]
	v_mfma_f32_16x16x32_bf16 v[4:7], v[164:167], v[210:213], v[4:7]
	v_mfma_f32_16x16x32_bf16 v[0:3], v[178:181], v[210:213], v[0:3]
	v_mfma_f32_16x16x32_bf16 v[52:55], v[168:171], v[190:193], v[52:55]
	v_mfma_f32_16x16x32_bf16 v[48:51], v[182:185], v[190:193], v[48:51]
	v_mfma_f32_16x16x32_bf16 v[36:39], v[168:171], v[198:201], v[36:39]
	v_mfma_f32_16x16x32_bf16 v[32:35], v[182:185], v[198:201], v[32:35]
	v_mfma_f32_16x16x32_bf16 v[20:23], v[168:171], v[206:209], v[20:23]
	v_mfma_f32_16x16x32_bf16 v[16:19], v[182:185], v[206:209], v[16:19]
	v_mfma_f32_16x16x32_bf16 v[4:7], v[168:171], v[214:217], v[4:7]
	v_mfma_f32_16x16x32_bf16 v[0:3], v[182:185], v[214:217], v[0:3]
	s_setprio 0
	s_barrier
	s_add_i32 s25, s25, 2
	s_add_u32 s42, s42, 0x100
	s_addc_u32 s43, s43, 0
	s_add_u32 s23, s23, 0x100
	s_addc_u32 s24, s24, 0
	s_cmp_gt_u32 s25, 13
	s_cbranch_scc0 .LBB5_248
	s_nop 0
	s_nop 0
	s_nop 0
	s_nop 0
	s_nop 0
	s_nop 0
	s_nop 0
	s_nop 0
	s_nop 0
	s_nop 0
	s_nop 0
	s_nop 0
	s_nop 0
	s_nop 0
	s_and_b64 vcc, exec, s[18:19]
	s_cbranch_vccz .LBB5_251
	s_barrier

.LBB5_463:
	ds_read_b128 v[64:67], v229
	ds_read_b128 v[68:71], v229 offset:1024
	ds_read_b128 v[72:75], v229 offset:2048
	ds_read_b128 v[76:79], v229 offset:3072
	ds_read_b128 v[136:139], v230
	ds_read_b128 v[140:143], v230 offset:1024
	ds_read_b128 v[144:147], v230 offset:2048
	ds_read_b128 v[148:151], v230 offset:3072
	s_add_u32 s35, s40, 0xfffc0080
	s_addc_u32 s42, s41, -1
	s_cmp_eq_u32 s34, 12
	s_cselect_b32 s45, s21, s42
	s_cselect_b32 s44, s24, s35
	s_cselect_b32 s43, s19, s33
	s_cselect_b32 s42, s25, s30
	v_lshl_add_u64 v[192:193], s[40:41], 0, v[208:209]
	s_add_i32 m0, s39, 0xc000
	ds_read_b128 v[160:163], v231
	ds_read_b128 v[164:167], v231 offset:1024
	ds_read_b128 v[168:171], v231 offset:2048
	ds_read_b128 v[172:175], v231 offset:3072
	ds_read_b128 v[176:179], v231 offset:4096
	ds_read_b128 v[180:183], v231 offset:5120
	ds_read_b128 v[184:187], v231 offset:6144
	ds_read_b128 v[188:191], v231 offset:7168
	global_load_lds_dwordx4 v[192:193], off
	v_lshl_add_u64 v[192:193], s[40:41], 0, v[210:211]
	s_add_i32 m0, s39, 0xe000
	s_nop 0
	global_load_lds_dwordx4 v[192:193], off
	s_cmp_eq_u32 s34, -2
	s_cbranch_scc1 .Lskw_P3
	s_waitcnt vmcnt(8)
.Lskw_P3:
	s_waitcnt lgkmcnt(0)
	s_barrier
	s_setprio 1
	s_waitcnt lgkmcnt(0)
	v_mfma_f32_16x16x32_bf16 v[156:159], v[64:67], v[160:163], v[156:159]
	v_mfma_f32_16x16x32_bf16 v[152:155], v[72:75], v[160:163], v[152:155]
	v_mfma_f32_16x16x32_bf16 v[124:127], v[64:67], v[168:171], v[124:127]
	v_mfma_f32_16x16x32_bf16 v[120:123], v[72:75], v[168:171], v[120:123]
	v_mfma_f32_16x16x32_bf16 v[108:111], v[64:67], v[176:179], v[108:111]
	v_mfma_f32_16x16x32_bf16 v[104:107], v[72:75], v[176:179], v[104:107]
	v_mfma_f32_16x16x32_bf16 v[92:95], v[64:67], v[184:187], v[92:95]
	v_mfma_f32_16x16x32_bf16 v[88:91], v[72:75], v[184:187], v[88:91]
	v_mfma_f32_16x16x32_bf16 v[156:159], v[68:71], v[164:167], v[156:159]
	v_mfma_f32_16x16x32_bf16 v[152:155], v[76:79], v[164:167], v[152:155]
	v_mfma_f32_16x16x32_bf16 v[124:127], v[68:71], v[172:175], v[124:127]
	v_mfma_f32_16x16x32_bf16 v[120:123], v[76:79], v[172:175], v[120:123]
	v_mfma_f32_16x16x32_bf16 v[108:111], v[68:71], v[180:183], v[108:111]
	v_mfma_f32_16x16x32_bf16 v[104:107], v[76:79], v[180:183], v[104:107]
	v_mfma_f32_16x16x32_bf16 v[92:95], v[68:71], v[188:191], v[92:95]
	v_mfma_f32_16x16x32_bf16 v[88:91], v[76:79], v[188:191], v[88:91]
	s_setprio 0
	s_setprio 1
	v_mfma_f32_16x16x32_bf16 v[132:135], v[136:139], v[160:163], v[132:135]
	v_mfma_f32_16x16x32_bf16 v[128:131], v[144:147], v[160:163], v[128:131]
	v_mfma_f32_16x16x32_bf16 v[116:119], v[136:139], v[168:171], v[116:119]
	v_mfma_f32_16x16x32_bf16 v[112:115], v[144:147], v[168:171], v[112:115]
	v_mfma_f32_16x16x32_bf16 v[100:103], v[136:139], v[176:179], v[100:103]
	v_mfma_f32_16x16x32_bf16 v[96:99], v[144:147], v[176:179], v[96:99]
	v_mfma_f32_16x16x32_bf16 v[84:87], v[136:139], v[184:187], v[84:87]
	v_mfma_f32_16x16x32_bf16 v[80:83], v[144:147], v[184:187], v[80:83]
	v_mfma_f32_16x16x32_bf16 v[132:135], v[140:143], v[164:167], v[132:135]
	v_mfma_f32_16x16x32_bf16 v[128:131], v[148:151], v[164:167], v[128:131]
	v_mfma_f32_16x16x32_bf16 v[116:119], v[140:143], v[172:175], v[116:119]
	v_mfma_f32_16x16x32_bf16 v[112:115], v[148:151], v[172:175], v[112:115]
	v_mfma_f32_16x16x32_bf16 v[100:103], v[140:143], v[180:183], v[100:103]
	v_mfma_f32_16x16x32_bf16 v[96:99], v[148:151], v[180:183], v[96:99]
	v_mfma_f32_16x16x32_bf16 v[84:87], v[140:143], v[188:191], v[84:87]
	v_mfma_f32_16x16x32_bf16 v[80:83], v[148:151], v[188:191], v[80:83]
	s_setprio 0
	s_barrier
	s_add_i32 s35, s55, s46
	v_lshl_add_u64 v[192:193], s[42:43], 0, v[202:203]
	s_mov_b32 m0, s35
	ds_read_b128 v[160:163], v231 offset:16384
	ds_read_b128 v[164:167], v231 offset:17408
	ds_read_b128 v[168:171], v231 offset:18432
	ds_read_b128 v[172:175], v231 offset:19456
	ds_read_b128 v[176:179], v231 offset:20480
	ds_read_b128 v[180:183], v231 offset:21504
	ds_read_b128 v[184:187], v231 offset:22528
	ds_read_b128 v[188:191], v231 offset:23552
	global_load_lds_dwordx4 v[192:193], off
	s_add_i32 m0, s35, 0x2000
	s_add_u32 s58, s42, 0x40000
	v_lshl_add_u64 v[194:195], s[42:43], 0, v[206:207]
	s_addc_u32 s59, s43, 0
	s_add_i32 s35, s56, s46
	global_load_lds_dwordx4 v[194:195], off
	v_lshl_add_u64 v[196:197], s[58:59], 0, v[202:203]
	s_mov_b32 m0, s35
	v_lshl_add_u64 v[198:199], s[44:45], 0, v[204:205]
	global_load_lds_dwordx4 v[196:197], off
	v_lshl_add_u64 v[196:197], s[58:59], 0, v[206:207]
	s_add_i32 m0, s35, 0x2000
	s_nop 0
	global_load_lds_dwordx4 v[196:197], off
	v_lshl_add_u64 v[196:197], s[44:45], 0, v[200:201]
	s_mov_b32 m0, s39
	s_nop 0
	global_load_lds_dwordx4 v[196:197], off
	s_mov_b32 m0, s48
	s_nop 0
	global_load_lds_dwordx4 v[198:199], off
	s_waitcnt vmcnt(8)
	s_waitcnt lgkmcnt(0)
	s_barrier
	s_setprio 1
	s_waitcnt lgkmcnt(0)
	v_mfma_f32_16x16x32_bf16 v[60:63], v[64:67], v[160:163], v[60:63]
	v_mfma_f32_16x16x32_bf16 v[56:59], v[72:75], v[160:163], v[56:59]
	v_mfma_f32_16x16x32_bf16 v[44:47], v[64:67], v[168:171], v[44:47]
	v_mfma_f32_16x16x32_bf16 v[40:43], v[72:75], v[168:171], v[40:43]
	v_mfma_f32_16x16x32_bf16 v[28:31], v[64:67], v[176:179], v[28:31]
	v_mfma_f32_16x16x32_bf16 v[24:27], v[72:75], v[176:179], v[24:27]
	v_mfma_f32_16x16x32_bf16 v[12:15], v[64:67], v[184:187], v[12:15]
	v_mfma_f32_16x16x32_bf16 v[8:11], v[72:75], v[184:187], v[8:11]
	v_mfma_f32_16x16x32_bf16 v[60:63], v[68:71], v[164:167], v[60:63]
	v_mfma_f32_16x16x32_bf16 v[56:59], v[76:79], v[164:167], v[56:59]
	v_mfma_f32_16x16x32_bf16 v[44:47], v[68:71], v[172:175], v[44:47]
	v_mfma_f32_16x16x32_bf16 v[40:43], v[76:79], v[172:175], v[40:43]
	v_mfma_f32_16x16x32_bf16 v[28:31], v[68:71], v[180:183], v[28:31]
	v_mfma_f32_16x16x32_bf16 v[24:27], v[76:79], v[180:183], v[24:27]
	v_mfma_f32_16x16x32_bf16 v[12:15], v[68:71], v[188:191], v[12:15]
	v_mfma_f32_16x16x32_bf16 v[8:11], v[76:79], v[188:191], v[8:11]
	s_setprio 0
	s_setprio 1
	v_mfma_f32_16x16x32_bf16 v[52:55], v[136:139], v[160:163], v[52:55]
	v_mfma_f32_16x16x32_bf16 v[48:51], v[144:147], v[160:163], v[48:51]
	v_mfma_f32_16x16x32_bf16 v[36:39], v[136:139], v[168:171], v[36:39]
	v_mfma_f32_16x16x32_bf16 v[32:35], v[144:147], v[168:171], v[32:35]
	v_mfma_f32_16x16x32_bf16 v[20:23], v[136:139], v[176:179], v[20:23]
	v_mfma_f32_16x16x32_bf16 v[16:19], v[144:147], v[176:179], v[16:19]
	v_mfma_f32_16x16x32_bf16 v[4:7], v[136:139], v[184:187], v[4:7]
	v_mfma_f32_16x16x32_bf16 v[0:3], v[144:147], v[184:187], v[0:3]
	v_mfma_f32_16x16x32_bf16 v[52:55], v[140:143], v[164:167], v[52:55]
	v_mfma_f32_16x16x32_bf16 v[48:51], v[148:151], v[164:167], v[48:51]
	v_mfma_f32_16x16x32_bf16 v[36:39], v[140:143], v[172:175], v[36:39]
	v_mfma_f32_16x16x32_bf16 v[32:35], v[148:151], v[172:175], v[32:35]
	v_mfma_f32_16x16x32_bf16 v[20:23], v[140:143], v[180:183], v[20:23]
	v_mfma_f32_16x16x32_bf16 v[16:19], v[148:151], v[180:183], v[16:19]
	v_mfma_f32_16x16x32_bf16 v[4:7], v[140:143], v[188:191], v[4:7]
	v_mfma_f32_16x16x32_bf16 v[0:3], v[148:151], v[188:191], v[0:3]
	s_setprio 0
	s_barrier
	s_add_i32 s35, 0, 0x18000
	s_add_i32 s57, 0, 0x1c000
	v_add_u32_e32 v76, s35, v227
	v_add_u32_e32 v148, s57, v227
	ds_read_b128 v[64:67], v76
	ds_read_b128 v[68:71], v76 offset:1024
	ds_read_b128 v[72:75], v76 offset:2048
	ds_read_b128 v[76:79], v76 offset:3072
	ds_read_b128 v[136:139], v148
	ds_read_b128 v[140:143], v148 offset:1024
	ds_read_b128 v[144:147], v148 offset:2048
	ds_read_b128 v[148:151], v148 offset:3072
	s_add_u32 s44, s44, 0x40000
	s_addc_u32 s45, s45, 0
	s_mov_b32 m0, s49
	v_lshl_add_u64 v[216:217], s[44:45], 0, v[200:201]
	ds_read_b128 v[160:163], v231 offset:32768
	ds_read_b128 v[164:167], v231 offset:33792
	ds_read_b128 v[168:171], v231 offset:34816
	ds_read_b128 v[172:175], v231 offset:35840
	ds_read_b128 v[176:179], v231 offset:36864
	ds_read_b128 v[180:183], v231 offset:37888
	ds_read_b128 v[184:187], v231 offset:38912
	ds_read_b128 v[188:191], v231 offset:39936
	global_load_lds_dwordx4 v[216:217], off
	v_lshl_add_u64 v[216:217], s[44:45], 0, v[204:205]
	s_mov_b32 m0, s50
	s_nop 0
	global_load_lds_dwordx4 v[216:217], off
	s_waitcnt vmcnt(8)
	s_waitcnt lgkmcnt(0)
	s_barrier
	s_setprio 1
	s_waitcnt lgkmcnt(0)
	v_mfma_f32_16x16x32_bf16 v[156:159], v[64:67], v[160:163], v[156:159]
	v_mfma_f32_16x16x32_bf16 v[152:155], v[72:75], v[160:163], v[152:155]
	v_mfma_f32_16x16x32_bf16 v[124:127], v[64:67], v[168:171], v[124:127]
	v_mfma_f32_16x16x32_bf16 v[120:123], v[72:75], v[168:171], v[120:123]
	v_mfma_f32_16x16x32_bf16 v[108:111], v[64:67], v[176:179], v[108:111]
	v_mfma_f32_16x16x32_bf16 v[104:107], v[72:75], v[176:179], v[104:107]
	v_mfma_f32_16x16x32_bf16 v[92:95], v[64:67], v[184:187], v[92:95]
	v_mfma_f32_16x16x32_bf16 v[88:91], v[72:75], v[184:187], v[88:91]
	v_mfma_f32_16x16x32_bf16 v[156:159], v[68:71], v[164:167], v[156:159]
	v_mfma_f32_16x16x32_bf16 v[152:155], v[76:79], v[164:167], v[152:155]
	v_mfma_f32_16x16x32_bf16 v[124:127], v[68:71], v[172:175], v[124:127]
	v_mfma_f32_16x16x32_bf16 v[120:123], v[76:79], v[172:175], v[120:123]
	v_mfma_f32_16x16x32_bf16 v[108:111], v[68:71], v[180:183], v[108:111]
	v_mfma_f32_16x16x32_bf16 v[104:107], v[76:79], v[180:183], v[104:107]
	v_mfma_f32_16x16x32_bf16 v[92:95], v[68:71], v[188:191], v[92:95]
	v_mfma_f32_16x16x32_bf16 v[88:91], v[76:79], v[188:191], v[88:91]
	s_setprio 0
	s_setprio 1
	v_mfma_f32_16x16x32_bf16 v[132:135], v[136:139], v[160:163], v[132:135]
	v_mfma_f32_16x16x32_bf16 v[128:131], v[144:147], v[160:163], v[128:131]
	v_mfma_f32_16x16x32_bf16 v[116:119], v[136:139], v[168:171], v[116:119]
	v_mfma_f32_16x16x32_bf16 v[112:115], v[144:147], v[168:171], v[112:115]
	v_mfma_f32_16x16x32_bf16 v[100:103], v[136:139], v[176:179], v[100:103]
	v_mfma_f32_16x16x32_bf16 v[96:99], v[144:147], v[176:179], v[96:99]
	v_mfma_f32_16x16x32_bf16 v[84:87], v[136:139], v[184:187], v[84:87]
	v_mfma_f32_16x16x32_bf16 v[80:83], v[144:147], v[184:187], v[80:83]
	v_mfma_f32_16x16x32_bf16 v[132:135], v[140:143], v[164:167], v[132:135]
	v_mfma_f32_16x16x32_bf16 v[128:131], v[148:151], v[164:167], v[128:131]
	v_mfma_f32_16x16x32_bf16 v[116:119], v[140:143], v[172:175], v[116:119]
	v_mfma_f32_16x16x32_bf16 v[112:115], v[148:151], v[172:175], v[112:115]
	v_mfma_f32_16x16x32_bf16 v[100:103], v[140:143], v[180:183], v[100:103]
	v_mfma_f32_16x16x32_bf16 v[96:99], v[148:151], v[180:183], v[96:99]
	v_mfma_f32_16x16x32_bf16 v[84:87], v[140:143], v[188:191], v[84:87]
	v_mfma_f32_16x16x32_bf16 v[80:83], v[148:151], v[188:191], v[80:83]
	s_setprio 0
	s_barrier
	s_add_i32 s35, s35, s46
	v_lshl_add_u64 v[192:193], v[192:193], 0, s[16:17]
	s_mov_b32 m0, s35
	ds_read_b128 v[160:163], v231 offset:49152
	ds_read_b128 v[164:167], v231 offset:50176
	ds_read_b128 v[168:171], v231 offset:51200
	ds_read_b128 v[172:175], v231 offset:52224
	ds_read_b128 v[176:179], v231 offset:53248
	ds_read_b128 v[180:183], v231 offset:54272
	ds_read_b128 v[184:187], v231 offset:55296
	ds_read_b128 v[188:191], v231 offset:56320
	global_load_lds_dwordx4 v[192:193], off
	s_add_i32 m0, s35, 0x2000
	s_add_u32 s42, s42, 0x40080
	v_lshl_add_u64 v[192:193], v[194:195], 0, s[16:17]
	s_addc_u32 s43, s43, 0
	s_add_i32 s35, s57, s46
	global_load_lds_dwordx4 v[192:193], off
	v_lshl_add_u64 v[192:193], s[42:43], 0, v[202:203]
	s_mov_b32 m0, s35
	s_nop 0
	global_load_lds_dwordx4 v[192:193], off
	v_lshl_add_u64 v[192:193], s[42:43], 0, v[206:207]
	s_add_i32 m0, s35, 0x2000
	s_nop 0
	global_load_lds_dwordx4 v[192:193], off
	v_lshl_add_u64 v[192:193], v[196:197], 0, s[16:17]
	s_mov_b32 m0, s53
	s_nop 0
	global_load_lds_dwordx4 v[192:193], off
	v_lshl_add_u64 v[192:193], v[198:199], 0, s[16:17]
	s_mov_b32 m0, s54
	s_nop 0
	global_load_lds_dwordx4 v[192:193], off
	s_waitcnt vmcnt(8)
	s_waitcnt lgkmcnt(0)
	s_barrier
	s_setprio 1
	s_waitcnt lgkmcnt(0)
	v_mfma_f32_16x16x32_bf16 v[60:63], v[64:67], v[160:163], v[60:63]
	v_mfma_f32_16x16x32_bf16 v[56:59], v[72:75], v[160:163], v[56:59]
	v_mfma_f32_16x16x32_bf16 v[44:47], v[64:67], v[168:171], v[44:47]
	v_mfma_f32_16x16x32_bf16 v[40:43], v[72:75], v[168:171], v[40:43]
	v_mfma_f32_16x16x32_bf16 v[28:31], v[64:67], v[176:179], v[28:31]
	v_mfma_f32_16x16x32_bf16 v[24:27], v[72:75], v[176:179], v[24:27]
	v_mfma_f32_16x16x32_bf16 v[12:15], v[64:67], v[184:187], v[12:15]
	v_mfma_f32_16x16x32_bf16 v[8:11], v[72:75], v[184:187], v[8:11]
	v_mfma_f32_16x16x32_bf16 v[60:63], v[68:71], v[164:167], v[60:63]
	v_mfma_f32_16x16x32_bf16 v[56:59], v[76:79], v[164:167], v[56:59]
	v_mfma_f32_16x16x32_bf16 v[44:47], v[68:71], v[172:175], v[44:47]
	v_mfma_f32_16x16x32_bf16 v[40:43], v[76:79], v[172:175], v[40:43]
	v_mfma_f32_16x16x32_bf16 v[28:31], v[68:71], v[180:183], v[28:31]
	v_mfma_f32_16x16x32_bf16 v[24:27], v[76:79], v[180:183], v[24:27]
	v_mfma_f32_16x16x32_bf16 v[12:15], v[68:71], v[188:191], v[12:15]
	v_mfma_f32_16x16x32_bf16 v[8:11], v[76:79], v[188:191], v[8:11]
	s_setprio 0
	s_setprio 1
	v_mfma_f32_16x16x32_bf16 v[52:55], v[136:139], v[160:163], v[52:55]
	v_mfma_f32_16x16x32_bf16 v[48:51], v[144:147], v[160:163], v[48:51]
	v_mfma_f32_16x16x32_bf16 v[36:39], v[136:139], v[168:171], v[36:39]
	v_mfma_f32_16x16x32_bf16 v[32:35], v[144:147], v[168:171], v[32:35]
	v_mfma_f32_16x16x32_bf16 v[20:23], v[136:139], v[176:179], v[20:23]
	v_mfma_f32_16x16x32_bf16 v[16:19], v[144:147], v[176:179], v[16:19]
	v_mfma_f32_16x16x32_bf16 v[4:7], v[136:139], v[184:187], v[4:7]
	v_mfma_f32_16x16x32_bf16 v[0:3], v[144:147], v[184:187], v[0:3]
	v_mfma_f32_16x16x32_bf16 v[52:55], v[140:143], v[164:167], v[52:55]
	v_mfma_f32_16x16x32_bf16 v[48:51], v[148:151], v[164:167], v[48:51]
	v_mfma_f32_16x16x32_bf16 v[36:39], v[140:143], v[172:175], v[36:39]
	v_mfma_f32_16x16x32_bf16 v[32:35], v[148:151], v[172:175], v[32:35]
	v_mfma_f32_16x16x32_bf16 v[20:23], v[140:143], v[180:183], v[20:23]
	v_mfma_f32_16x16x32_bf16 v[16:19], v[148:151], v[180:183], v[16:19]
	v_mfma_f32_16x16x32_bf16 v[4:7], v[140:143], v[188:191], v[4:7]
	v_mfma_f32_16x16x32_bf16 v[0:3], v[148:151], v[188:191], v[0:3]
	s_setprio 0
	s_barrier
	s_add_i32 s34, s34, 2
	s_add_u32 s40, s40, 0x100
	s_addc_u32 s41, s41, 0
	s_add_u32 s30, s30, 0x100
	s_addc_u32 s33, s33, 0
	s_cmp_gt_u32 s34, 13
	s_cbranch_scc0 .LBB5_463
	s_nop 0
	s_nop 0
	s_nop 0
	s_nop 0
	s_nop 0
	s_nop 0
	s_nop 0
	s_nop 0
	s_nop 0
	s_nop 0
	s_nop 0
	s_nop 0
	s_nop 0
	s_nop 0
	s_and_b64 vcc, exec, s[14:15]
	s_cbranch_vccz .LBB5_466
	s_barrier

.LBB5_536:
	ds_read_b128 v[128:131], v209
	ds_read_b128 v[132:135], v209 offset:1024
	ds_read_b128 v[136:139], v209 offset:2048
	ds_read_b128 v[140:143], v209 offset:3072
	ds_read_b128 v[144:147], v210
	ds_read_b128 v[148:151], v210 offset:1024
	ds_read_b128 v[152:155], v210 offset:2048
	ds_read_b128 v[156:159], v210 offset:3072
	s_add_u32 s42, s40, 0xfffc0080
	s_addc_u32 s43, s41, -1
	s_cmp_eq_u32 s57, 12
	s_cselect_b32 s45, s21, s43
	s_cselect_b32 s44, s39, s42
	s_cselect_b32 s43, s19, s56
	s_cselect_b32 s42, s54, s55
	v_lshl_add_u64 v[216:217], s[40:41], 0, v[184:185]
	s_add_i32 m0, s31, 0xc000
	ds_read_b128 v[160:163], v211
	ds_read_b128 v[164:167], v211 offset:1024
	ds_read_b128 v[168:171], v211 offset:2048
	ds_read_b128 v[172:175], v211 offset:3072
	ds_read_b128 v[192:195], v211 offset:4096
	ds_read_b128 v[196:199], v211 offset:5120
	ds_read_b128 v[200:203], v211 offset:6144
	ds_read_b128 v[212:215], v211 offset:7168
	global_load_lds_dwordx4 v[216:217], off
	v_lshl_add_u64 v[216:217], s[40:41], 0, v[186:187]
	s_add_i32 m0, s31, 0xe000
	s_nop 0
	global_load_lds_dwordx4 v[216:217], off
	s_cmp_eq_u32 s57, -2
	s_cbranch_scc1 .Lskw_P4
	s_waitcnt vmcnt(8)
.Lskw_P4:
	s_waitcnt lgkmcnt(0)
	s_barrier
	s_setprio 1
	s_waitcnt lgkmcnt(0)
	v_mfma_f32_16x16x32_bf16 v[124:127], v[128:131], v[160:163], v[124:127]
	v_mfma_f32_16x16x32_bf16 v[120:123], v[136:139], v[160:163], v[120:123]
	v_mfma_f32_16x16x32_bf16 v[108:111], v[128:131], v[168:171], v[108:111]
	v_mfma_f32_16x16x32_bf16 v[104:107], v[136:139], v[168:171], v[104:107]
	v_mfma_f32_16x16x32_bf16 v[92:95], v[128:131], v[192:195], v[92:95]
	v_mfma_f32_16x16x32_bf16 v[88:91], v[136:139], v[192:195], v[88:91]
	v_mfma_f32_16x16x32_bf16 v[76:79], v[128:131], v[200:203], v[76:79]
	v_mfma_f32_16x16x32_bf16 v[72:75], v[136:139], v[200:203], v[72:75]
	v_mfma_f32_16x16x32_bf16 v[124:127], v[132:135], v[164:167], v[124:127]
	v_mfma_f32_16x16x32_bf16 v[120:123], v[140:143], v[164:167], v[120:123]
	v_mfma_f32_16x16x32_bf16 v[108:111], v[132:135], v[172:175], v[108:111]
	v_mfma_f32_16x16x32_bf16 v[104:107], v[140:143], v[172:175], v[104:107]
	v_mfma_f32_16x16x32_bf16 v[92:95], v[132:135], v[196:199], v[92:95]
	v_mfma_f32_16x16x32_bf16 v[88:91], v[140:143], v[196:199], v[88:91]
	v_mfma_f32_16x16x32_bf16 v[76:79], v[132:135], v[212:215], v[76:79]
	v_mfma_f32_16x16x32_bf16 v[72:75], v[140:143], v[212:215], v[72:75]
	s_setprio 0
	s_setprio 1
	v_mfma_f32_16x16x32_bf16 v[116:119], v[144:147], v[160:163], v[116:119]
	v_mfma_f32_16x16x32_bf16 v[112:115], v[152:155], v[160:163], v[112:115]
	v_mfma_f32_16x16x32_bf16 v[100:103], v[144:147], v[168:171], v[100:103]
	v_mfma_f32_16x16x32_bf16 v[96:99], v[152:155], v[168:171], v[96:99]
	v_mfma_f32_16x16x32_bf16 v[84:87], v[144:147], v[192:195], v[84:87]
	v_mfma_f32_16x16x32_bf16 v[80:83], v[152:155], v[192:195], v[80:83]
	v_mfma_f32_16x16x32_bf16 v[68:71], v[144:147], v[200:203], v[68:71]
	v_mfma_f32_16x16x32_bf16 v[64:67], v[152:155], v[200:203], v[64:67]
	v_mfma_f32_16x16x32_bf16 v[116:119], v[148:151], v[164:167], v[116:119]
	v_mfma_f32_16x16x32_bf16 v[112:115], v[156:159], v[164:167], v[112:115]
	v_mfma_f32_16x16x32_bf16 v[100:103], v[148:151], v[172:175], v[100:103]
	v_mfma_f32_16x16x32_bf16 v[96:99], v[156:159], v[172:175], v[96:99]
	v_mfma_f32_16x16x32_bf16 v[84:87], v[148:151], v[196:199], v[84:87]
	v_mfma_f32_16x16x32_bf16 v[80:83], v[156:159], v[196:199], v[80:83]
	v_mfma_f32_16x16x32_bf16 v[68:71], v[148:151], v[212:215], v[68:71]
	v_mfma_f32_16x16x32_bf16 v[64:67], v[156:159], v[212:215], v[64:67]
	s_setprio 0
	s_barrier
	s_add_i32 s58, s51, s30
	v_lshl_add_u64 v[216:217], s[42:43], 0, v[178:179]
	s_mov_b32 m0, s58
	ds_read_b128 v[160:163], v211 offset:16384
	ds_read_b128 v[164:167], v211 offset:17408
	ds_read_b128 v[168:171], v211 offset:18432
	ds_read_b128 v[172:175], v211 offset:19456
	ds_read_b128 v[192:195], v211 offset:20480
	ds_read_b128 v[196:199], v211 offset:21504
	ds_read_b128 v[200:203], v211 offset:22528
	ds_read_b128 v[212:215], v211 offset:23552
	global_load_lds_dwordx4 v[216:217], off
	s_add_i32 m0, s58, 0x2000
	s_add_u32 s58, s42, 0x40000
	v_lshl_add_u64 v[218:219], s[42:43], 0, v[182:183]
	s_addc_u32 s59, s43, 0
	s_add_i32 s60, s52, s30
	global_load_lds_dwordx4 v[218:219], off
	v_lshl_add_u64 v[220:221], s[58:59], 0, v[178:179]
	s_mov_b32 m0, s60
	v_lshl_add_u64 v[222:223], s[44:45], 0, v[180:181]
	global_load_lds_dwordx4 v[220:221], off
	v_lshl_add_u64 v[220:221], s[58:59], 0, v[182:183]
	s_add_i32 m0, s60, 0x2000
	s_nop 0
	global_load_lds_dwordx4 v[220:221], off
	v_lshl_add_u64 v[220:221], s[44:45], 0, v[176:177]
	s_mov_b32 m0, s31
	s_nop 0
	global_load_lds_dwordx4 v[220:221], off
	s_mov_b32 m0, s33
	s_nop 0
	global_load_lds_dwordx4 v[222:223], off
	s_waitcnt vmcnt(8)
	s_waitcnt lgkmcnt(0)
	s_barrier
	s_setprio 1
	s_waitcnt lgkmcnt(0)
	v_mfma_f32_16x16x32_bf16 v[60:63], v[128:131], v[160:163], v[60:63]
	v_mfma_f32_16x16x32_bf16 v[56:59], v[136:139], v[160:163], v[56:59]
	v_mfma_f32_16x16x32_bf16 v[44:47], v[128:131], v[168:171], v[44:47]
	v_mfma_f32_16x16x32_bf16 v[40:43], v[136:139], v[168:171], v[40:43]
	v_mfma_f32_16x16x32_bf16 v[28:31], v[128:131], v[192:195], v[28:31]
	v_mfma_f32_16x16x32_bf16 v[24:27], v[136:139], v[192:195], v[24:27]
	v_mfma_f32_16x16x32_bf16 v[12:15], v[128:131], v[200:203], v[12:15]
	v_mfma_f32_16x16x32_bf16 v[8:11], v[136:139], v[200:203], v[8:11]
	v_mfma_f32_16x16x32_bf16 v[60:63], v[132:135], v[164:167], v[60:63]
	v_mfma_f32_16x16x32_bf16 v[56:59], v[140:143], v[164:167], v[56:59]
	v_mfma_f32_16x16x32_bf16 v[44:47], v[132:135], v[172:175], v[44:47]
	v_mfma_f32_16x16x32_bf16 v[40:43], v[140:143], v[172:175], v[40:43]
	v_mfma_f32_16x16x32_bf16 v[28:31], v[132:135], v[196:199], v[28:31]
	v_mfma_f32_16x16x32_bf16 v[24:27], v[140:143], v[196:199], v[24:27]
	v_mfma_f32_16x16x32_bf16 v[12:15], v[132:135], v[212:215], v[12:15]
	v_mfma_f32_16x16x32_bf16 v[8:11], v[140:143], v[212:215], v[8:11]
	s_setprio 0
	s_setprio 1
	v_mfma_f32_16x16x32_bf16 v[52:55], v[144:147], v[160:163], v[52:55]
	v_mfma_f32_16x16x32_bf16 v[48:51], v[152:155], v[160:163], v[48:51]
	v_mfma_f32_16x16x32_bf16 v[36:39], v[144:147], v[168:171], v[36:39]
	v_mfma_f32_16x16x32_bf16 v[32:35], v[152:155], v[168:171], v[32:35]
	v_mfma_f32_16x16x32_bf16 v[20:23], v[144:147], v[192:195], v[20:23]
	v_mfma_f32_16x16x32_bf16 v[16:19], v[152:155], v[192:195], v[16:19]
	v_mfma_f32_16x16x32_bf16 v[4:7], v[144:147], v[200:203], v[4:7]
	v_mfma_f32_16x16x32_bf16 v[0:3], v[152:155], v[200:203], v[0:3]
	v_mfma_f32_16x16x32_bf16 v[52:55], v[148:151], v[164:167], v[52:55]
	v_mfma_f32_16x16x32_bf16 v[48:51], v[156:159], v[164:167], v[48:51]
	v_mfma_f32_16x16x32_bf16 v[36:39], v[148:151], v[172:175], v[36:39]
	v_mfma_f32_16x16x32_bf16 v[32:35], v[156:159], v[172:175], v[32:35]
	v_mfma_f32_16x16x32_bf16 v[20:23], v[148:151], v[196:199], v[20:23]
	v_mfma_f32_16x16x32_bf16 v[16:19], v[156:159], v[196:199], v[16:19]
	v_mfma_f32_16x16x32_bf16 v[4:7], v[148:151], v[212:215], v[4:7]
	v_mfma_f32_16x16x32_bf16 v[0:3], v[156:159], v[212:215], v[0:3]
	s_setprio 0
	s_barrier
	s_add_i32 s58, 0, 0x18000
	s_add_i32 s59, 0, 0x1c000
	v_add_u32_e32 v140, s58, v205
	v_add_u32_e32 v156, s59, v205
	ds_read_b128 v[128:131], v140
	ds_read_b128 v[132:135], v140 offset:1024
	ds_read_b128 v[136:139], v140 offset:2048
	ds_read_b128 v[140:143], v140 offset:3072
	ds_read_b128 v[144:147], v156
	ds_read_b128 v[148:151], v156 offset:1024
	ds_read_b128 v[152:155], v156 offset:2048
	ds_read_b128 v[156:159], v156 offset:3072
	s_add_u32 s44, s44, 0x40000
	s_addc_u32 s45, s45, 0
	s_mov_b32 m0, s34
	v_lshl_add_u64 v[224:225], s[44:45], 0, v[176:177]
	ds_read_b128 v[160:163], v211 offset:32768
	ds_read_b128 v[164:167], v211 offset:33792
	ds_read_b128 v[168:171], v211 offset:34816
	ds_read_b128 v[172:175], v211 offset:35840
	ds_read_b128 v[192:195], v211 offset:36864
	ds_read_b128 v[196:199], v211 offset:37888
	ds_read_b128 v[200:203], v211 offset:38912
	ds_read_b128 v[212:215], v211 offset:39936
	global_load_lds_dwordx4 v[224:225], off
	v_lshl_add_u64 v[224:225], s[44:45], 0, v[180:181]
	s_mov_b32 m0, s35
	s_nop 0
	global_load_lds_dwordx4 v[224:225], off
	s_waitcnt vmcnt(8)
	s_waitcnt lgkmcnt(0)
	s_barrier
	s_setprio 1
	s_waitcnt lgkmcnt(0)
	v_mfma_f32_16x16x32_bf16 v[124:127], v[128:131], v[160:163], v[124:127]
	v_mfma_f32_16x16x32_bf16 v[120:123], v[136:139], v[160:163], v[120:123]
	v_mfma_f32_16x16x32_bf16 v[108:111], v[128:131], v[168:171], v[108:111]
	v_mfma_f32_16x16x32_bf16 v[104:107], v[136:139], v[168:171], v[104:107]
	v_mfma_f32_16x16x32_bf16 v[92:95], v[128:131], v[192:195], v[92:95]
	v_mfma_f32_16x16x32_bf16 v[88:91], v[136:139], v[192:195], v[88:91]
	v_mfma_f32_16x16x32_bf16 v[76:79], v[128:131], v[200:203], v[76:79]
	v_mfma_f32_16x16x32_bf16 v[72:75], v[136:139], v[200:203], v[72:75]
	v_mfma_f32_16x16x32_bf16 v[124:127], v[132:135], v[164:167], v[124:127]
	v_mfma_f32_16x16x32_bf16 v[120:123], v[140:143], v[164:167], v[120:123]
	v_mfma_f32_16x16x32_bf16 v[108:111], v[132:135], v[172:175], v[108:111]
	v_mfma_f32_16x16x32_bf16 v[104:107], v[140:143], v[172:175], v[104:107]
	v_mfma_f32_16x16x32_bf16 v[92:95], v[132:135], v[196:199], v[92:95]
	v_mfma_f32_16x16x32_bf16 v[88:91], v[140:143], v[196:199], v[88:91]
	v_mfma_f32_16x16x32_bf16 v[76:79], v[132:135], v[212:215], v[76:79]
	v_mfma_f32_16x16x32_bf16 v[72:75], v[140:143], v[212:215], v[72:75]
	s_setprio 0
	s_setprio 1
	v_mfma_f32_16x16x32_bf16 v[116:119], v[144:147], v[160:163], v[116:119]
	v_mfma_f32_16x16x32_bf16 v[112:115], v[152:155], v[160:163], v[112:115]
	v_mfma_f32_16x16x32_bf16 v[100:103], v[144:147], v[168:171], v[100:103]
	v_mfma_f32_16x16x32_bf16 v[96:99], v[152:155], v[168:171], v[96:99]
	v_mfma_f32_16x16x32_bf16 v[84:87], v[144:147], v[192:195], v[84:87]
	v_mfma_f32_16x16x32_bf16 v[80:83], v[152:155], v[192:195], v[80:83]
	v_mfma_f32_16x16x32_bf16 v[68:71], v[144:147], v[200:203], v[68:71]
	v_mfma_f32_16x16x32_bf16 v[64:67], v[152:155], v[200:203], v[64:67]
	v_mfma_f32_16x16x32_bf16 v[116:119], v[148:151], v[164:167], v[116:119]
	v_mfma_f32_16x16x32_bf16 v[112:115], v[156:159], v[164:167], v[112:115]
	v_mfma_f32_16x16x32_bf16 v[100:103], v[148:151], v[172:175], v[100:103]
	v_mfma_f32_16x16x32_bf16 v[96:99], v[156:159], v[172:175], v[96:99]
	v_mfma_f32_16x16x32_bf16 v[84:87], v[148:151], v[196:199], v[84:87]
	v_mfma_f32_16x16x32_bf16 v[80:83], v[156:159], v[196:199], v[80:83]
	v_mfma_f32_16x16x32_bf16 v[68:71], v[148:151], v[212:215], v[68:71]
	v_mfma_f32_16x16x32_bf16 v[64:67], v[156:159], v[212:215], v[64:67]
	s_setprio 0
	s_barrier
	s_add_i32 s44, s58, s30
	v_lshl_add_u64 v[216:217], v[216:217], 0, s[16:17]
	s_mov_b32 m0, s44
	ds_read_b128 v[160:163], v211 offset:49152
	ds_read_b128 v[164:167], v211 offset:50176
	ds_read_b128 v[168:171], v211 offset:51200
	ds_read_b128 v[172:175], v211 offset:52224
	ds_read_b128 v[192:195], v211 offset:53248
	ds_read_b128 v[196:199], v211 offset:54272
	ds_read_b128 v[200:203], v211 offset:55296
	ds_read_b128 v[212:215], v211 offset:56320
	global_load_lds_dwordx4 v[216:217], off
	s_add_i32 m0, s44, 0x2000
	s_add_u32 s42, s42, 0x40080
	v_lshl_add_u64 v[216:217], v[218:219], 0, s[16:17]
	s_addc_u32 s43, s43, 0
	s_add_i32 s44, s59, s30
	global_load_lds_dwordx4 v[216:217], off
	v_lshl_add_u64 v[216:217], s[42:43], 0, v[178:179]
	s_mov_b32 m0, s44
	s_nop 0
	global_load_lds_dwordx4 v[216:217], off
	v_lshl_add_u64 v[216:217], s[42:43], 0, v[182:183]
	s_add_i32 m0, s44, 0x2000
	s_nop 0
	global_load_lds_dwordx4 v[216:217], off
	v_lshl_add_u64 v[216:217], v[220:221], 0, s[16:17]
	s_mov_b32 m0, s49
	s_nop 0
	global_load_lds_dwordx4 v[216:217], off
	v_lshl_add_u64 v[216:217], v[222:223], 0, s[16:17]
	s_mov_b32 m0, s50
	s_nop 0
	global_load_lds_dwordx4 v[216:217], off
	s_waitcnt vmcnt(8)
	s_waitcnt lgkmcnt(0)
	s_barrier
	s_setprio 1
	s_waitcnt lgkmcnt(0)
	v_mfma_f32_16x16x32_bf16 v[60:63], v[128:131], v[160:163], v[60:63]
	v_mfma_f32_16x16x32_bf16 v[56:59], v[136:139], v[160:163], v[56:59]
	v_mfma_f32_16x16x32_bf16 v[44:47], v[128:131], v[168:171], v[44:47]
	v_mfma_f32_16x16x32_bf16 v[40:43], v[136:139], v[168:171], v[40:43]
	v_mfma_f32_16x16x32_bf16 v[28:31], v[128:131], v[192:195], v[28:31]
	v_mfma_f32_16x16x32_bf16 v[24:27], v[136:139], v[192:195], v[24:27]
	v_mfma_f32_16x16x32_bf16 v[12:15], v[128:131], v[200:203], v[12:15]
	v_mfma_f32_16x16x32_bf16 v[8:11], v[136:139], v[200:203], v[8:11]
	v_mfma_f32_16x16x32_bf16 v[60:63], v[132:135], v[164:167], v[60:63]
	v_mfma_f32_16x16x32_bf16 v[56:59], v[140:143], v[164:167], v[56:59]
	v_mfma_f32_16x16x32_bf16 v[44:47], v[132:135], v[172:175], v[44:47]
	v_mfma_f32_16x16x32_bf16 v[40:43], v[140:143], v[172:175], v[40:43]
	v_mfma_f32_16x16x32_bf16 v[28:31], v[132:135], v[196:199], v[28:31]
	v_mfma_f32_16x16x32_bf16 v[24:27], v[140:143], v[196:199], v[24:27]
	v_mfma_f32_16x16x32_bf16 v[12:15], v[132:135], v[212:215], v[12:15]
	v_mfma_f32_16x16x32_bf16 v[8:11], v[140:143], v[212:215], v[8:11]
	s_setprio 0
	s_setprio 1
	v_mfma_f32_16x16x32_bf16 v[52:55], v[144:147], v[160:163], v[52:55]
	v_mfma_f32_16x16x32_bf16 v[48:51], v[152:155], v[160:163], v[48:51]
	v_mfma_f32_16x16x32_bf16 v[36:39], v[144:147], v[168:171], v[36:39]
	v_mfma_f32_16x16x32_bf16 v[32:35], v[152:155], v[168:171], v[32:35]
	v_mfma_f32_16x16x32_bf16 v[20:23], v[144:147], v[192:195], v[20:23]
	v_mfma_f32_16x16x32_bf16 v[16:19], v[152:155], v[192:195], v[16:19]
	v_mfma_f32_16x16x32_bf16 v[4:7], v[144:147], v[200:203], v[4:7]
	v_mfma_f32_16x16x32_bf16 v[0:3], v[152:155], v[200:203], v[0:3]
	v_mfma_f32_16x16x32_bf16 v[52:55], v[148:151], v[164:167], v[52:55]
	v_mfma_f32_16x16x32_bf16 v[48:51], v[156:159], v[164:167], v[48:51]
	v_mfma_f32_16x16x32_bf16 v[36:39], v[148:151], v[172:175], v[36:39]
	v_mfma_f32_16x16x32_bf16 v[32:35], v[156:159], v[172:175], v[32:35]
	v_mfma_f32_16x16x32_bf16 v[20:23], v[148:151], v[196:199], v[20:23]
	v_mfma_f32_16x16x32_bf16 v[16:19], v[156:159], v[196:199], v[16:19]
	v_mfma_f32_16x16x32_bf16 v[4:7], v[148:151], v[212:215], v[4:7]
	v_mfma_f32_16x16x32_bf16 v[0:3], v[156:159], v[212:215], v[0:3]
	s_setprio 0
	s_barrier
	s_add_i32 s57, s57, 2
	s_add_u32 s40, s40, 0x100
	s_addc_u32 s41, s41, 0
	s_add_u32 s55, s55, 0x100
	s_addc_u32 s56, s56, 0
	s_cmp_gt_u32 s57, 13
	s_cbranch_scc0 .LBB5_536
	s_nop 0
	s_nop 0
	s_nop 0
	s_nop 0
	s_nop 0
	s_nop 0
	s_nop 0
	s_nop 0
	s_nop 0
	s_nop 0
	s_nop 0
	s_nop 0
	s_nop 0
	s_nop 0
	s_and_b64 vcc, exec, s[14:15]
	s_cbranch_vccz .LBB5_539
	s_barrier

.LBB5_625:
	ds_read_b128 v[32:35], v186
	ds_read_b128 v[36:39], v186 offset:1024
	ds_read_b128 v[40:43], v186 offset:2048
	ds_read_b128 v[44:47], v186 offset:3072
	ds_read_b128 v[144:147], v187
	ds_read_b128 v[148:151], v187 offset:1024
	ds_read_b128 v[152:155], v187 offset:2048
	ds_read_b128 v[156:159], v187 offset:3072
	s_add_u32 s8, s6, 0xfffc0080
	s_addc_u32 s9, s7, -1
	s_cmp_eq_u32 s33, 12
	s_cselect_b32 s57, s3, s9
	s_cselect_b32 s56, s5, s8
	s_cselect_b32 s9, s13, s30
	s_cselect_b32 s8, s24, s25
	v_lshl_add_u64 v[180:181], s[6:7], 0, v[172:173]
	s_add_i32 m0, s61, 0xc000
	ds_read_b128 v[192:195], v188
	ds_read_b128 v[196:199], v188 offset:1024
	ds_read_b128 v[200:203], v188 offset:2048
	ds_read_b128 v[204:207], v188 offset:3072
	ds_read_b128 v[208:211], v188 offset:4096
	ds_read_b128 v[212:215], v188 offset:5120
	ds_read_b128 v[216:219], v188 offset:6144
	ds_read_b128 v[220:223], v188 offset:7168
	global_load_lds_dwordx4 v[180:181], off
	v_lshl_add_u64 v[180:181], s[6:7], 0, v[174:175]
	s_add_i32 m0, s61, 0xe000
	s_nop 0
	global_load_lds_dwordx4 v[180:181], off
	s_cmp_eq_u32 s33, -2
	s_cbranch_scc1 .Lskw_P5
	s_waitcnt vmcnt(8)
.Lskw_P5:
	s_waitcnt lgkmcnt(0)
	s_barrier
	s_setprio 1
	s_waitcnt lgkmcnt(0)
	v_mfma_f32_16x16x32_bf16 v[140:143], v[32:35], v[192:195], v[140:143]
	v_mfma_f32_16x16x32_bf16 v[136:139], v[40:43], v[192:195], v[136:139]
	v_mfma_f32_16x16x32_bf16 v[124:127], v[32:35], v[200:203], v[124:127]
	v_mfma_f32_16x16x32_bf16 v[120:123], v[40:43], v[200:203], v[120:123]
	v_mfma_f32_16x16x32_bf16 v[108:111], v[32:35], v[208:211], v[108:111]
	v_mfma_f32_16x16x32_bf16 v[104:107], v[40:43], v[208:211], v[104:107]
	v_mfma_f32_16x16x32_bf16 v[92:95], v[32:35], v[216:219], v[92:95]
	v_mfma_f32_16x16x32_bf16 v[88:91], v[40:43], v[216:219], v[88:91]
	v_mfma_f32_16x16x32_bf16 v[140:143], v[36:39], v[196:199], v[140:143]
	v_mfma_f32_16x16x32_bf16 v[136:139], v[44:47], v[196:199], v[136:139]
	v_mfma_f32_16x16x32_bf16 v[124:127], v[36:39], v[204:207], v[124:127]
	v_mfma_f32_16x16x32_bf16 v[120:123], v[44:47], v[204:207], v[120:123]
	v_mfma_f32_16x16x32_bf16 v[108:111], v[36:39], v[212:215], v[108:111]
	v_mfma_f32_16x16x32_bf16 v[104:107], v[44:47], v[212:215], v[104:107]
	v_mfma_f32_16x16x32_bf16 v[92:95], v[36:39], v[220:223], v[92:95]
	v_mfma_f32_16x16x32_bf16 v[88:91], v[44:47], v[220:223], v[88:91]
	s_setprio 0
	s_setprio 1
	v_mfma_f32_16x16x32_bf16 v[132:135], v[144:147], v[192:195], v[132:135]
	v_mfma_f32_16x16x32_bf16 v[128:131], v[152:155], v[192:195], v[128:131]
	v_mfma_f32_16x16x32_bf16 v[116:119], v[144:147], v[200:203], v[116:119]
	v_mfma_f32_16x16x32_bf16 v[112:115], v[152:155], v[200:203], v[112:115]
	v_mfma_f32_16x16x32_bf16 v[100:103], v[144:147], v[208:211], v[100:103]
	v_mfma_f32_16x16x32_bf16 v[96:99], v[152:155], v[208:211], v[96:99]
	v_mfma_f32_16x16x32_bf16 v[84:87], v[144:147], v[216:219], v[84:87]
	v_mfma_f32_16x16x32_bf16 v[80:83], v[152:155], v[216:219], v[80:83]
	v_mfma_f32_16x16x32_bf16 v[132:135], v[148:151], v[196:199], v[132:135]
	v_mfma_f32_16x16x32_bf16 v[128:131], v[156:159], v[196:199], v[128:131]
	v_mfma_f32_16x16x32_bf16 v[116:119], v[148:151], v[204:207], v[116:119]
	v_mfma_f32_16x16x32_bf16 v[112:115], v[156:159], v[204:207], v[112:115]
	v_mfma_f32_16x16x32_bf16 v[100:103], v[148:151], v[212:215], v[100:103]
	v_mfma_f32_16x16x32_bf16 v[96:99], v[156:159], v[212:215], v[96:99]
	v_mfma_f32_16x16x32_bf16 v[84:87], v[148:151], v[220:223], v[84:87]
	v_mfma_f32_16x16x32_bf16 v[80:83], v[156:159], v[220:223], v[80:83]
	s_setprio 0
	s_barrier
	s_add_i32 s34, s80, s60
	v_lshl_add_u64 v[180:181], s[8:9], 0, v[162:163]
	s_mov_b32 m0, s34
	ds_read_b128 v[192:195], v188 offset:16384
	ds_read_b128 v[196:199], v188 offset:17408
	ds_read_b128 v[200:203], v188 offset:18432
	ds_read_b128 v[204:207], v188 offset:19456
	ds_read_b128 v[208:211], v188 offset:20480
	ds_read_b128 v[212:215], v188 offset:21504
	ds_read_b128 v[216:219], v188 offset:22528
	ds_read_b128 v[220:223], v188 offset:23552
	global_load_lds_dwordx4 v[180:181], off
	s_add_i32 m0, s34, 0x2000
	s_add_u32 s34, s8, 0x40000
	v_lshl_add_u64 v[224:225], s[8:9], 0, v[166:167]
	s_addc_u32 s35, s9, 0
	s_add_i32 s49, s81, s60
	global_load_lds_dwordx4 v[224:225], off
	v_lshl_add_u64 v[226:227], s[34:35], 0, v[162:163]
	s_mov_b32 m0, s49
	v_lshl_add_u64 v[228:229], s[56:57], 0, v[164:165]
	global_load_lds_dwordx4 v[226:227], off
	v_lshl_add_u64 v[226:227], s[34:35], 0, v[166:167]
	s_add_i32 m0, s49, 0x2000
	s_nop 0
	global_load_lds_dwordx4 v[226:227], off
	v_lshl_add_u64 v[226:227], s[56:57], 0, v[160:161]
	s_mov_b32 m0, s61
	s_nop 0
	global_load_lds_dwordx4 v[226:227], off
	s_mov_b32 m0, s62
	s_nop 0
	global_load_lds_dwordx4 v[228:229], off
	s_waitcnt vmcnt(8)
	s_waitcnt lgkmcnt(0)
	s_barrier
	s_setprio 1
	s_waitcnt lgkmcnt(0)
	v_mfma_f32_16x16x32_bf16 v[76:79], v[32:35], v[192:195], v[76:79]
	v_mfma_f32_16x16x32_bf16 v[72:75], v[40:43], v[192:195], v[72:75]
	v_mfma_f32_16x16x32_bf16 v[60:63], v[32:35], v[200:203], v[60:63]
	v_mfma_f32_16x16x32_bf16 v[56:59], v[40:43], v[200:203], v[56:59]
	v_mfma_f32_16x16x32_bf16 v[28:31], v[32:35], v[208:211], v[28:31]
	v_mfma_f32_16x16x32_bf16 v[24:27], v[40:43], v[208:211], v[24:27]
	v_mfma_f32_16x16x32_bf16 v[12:15], v[32:35], v[216:219], v[12:15]
	v_mfma_f32_16x16x32_bf16 v[8:11], v[40:43], v[216:219], v[8:11]
	v_mfma_f32_16x16x32_bf16 v[76:79], v[36:39], v[196:199], v[76:79]
	v_mfma_f32_16x16x32_bf16 v[72:75], v[44:47], v[196:199], v[72:75]
	v_mfma_f32_16x16x32_bf16 v[60:63], v[36:39], v[204:207], v[60:63]
	v_mfma_f32_16x16x32_bf16 v[56:59], v[44:47], v[204:207], v[56:59]
	v_mfma_f32_16x16x32_bf16 v[28:31], v[36:39], v[212:215], v[28:31]
	v_mfma_f32_16x16x32_bf16 v[24:27], v[44:47], v[212:215], v[24:27]
	v_mfma_f32_16x16x32_bf16 v[12:15], v[36:39], v[220:223], v[12:15]
	v_mfma_f32_16x16x32_bf16 v[8:11], v[44:47], v[220:223], v[8:11]
	s_setprio 0
	s_setprio 1
	v_mfma_f32_16x16x32_bf16 v[20:23], v[144:147], v[208:211], v[20:23]
	v_mfma_f32_16x16x32_bf16 v[16:19], v[152:155], v[208:211], v[16:19]
	v_mfma_f32_16x16x32_bf16 v[4:7], v[144:147], v[216:219], v[4:7]
	v_mfma_f32_16x16x32_bf16 v[0:3], v[152:155], v[216:219], v[0:3]
	v_mfma_f32_16x16x32_bf16 v[32:35], v[144:147], v[192:195], v[68:71]
	v_mfma_f32_16x16x32_bf16 v[36:39], v[152:155], v[192:195], v[64:67]
	v_mfma_f32_16x16x32_bf16 v[40:43], v[144:147], v[200:203], v[52:55]
	v_mfma_f32_16x16x32_bf16 v[44:47], v[152:155], v[200:203], v[48:51]
	v_mfma_f32_16x16x32_bf16 v[20:23], v[148:151], v[212:215], v[20:23]
	v_mfma_f32_16x16x32_bf16 v[16:19], v[156:159], v[212:215], v[16:19]
	v_mfma_f32_16x16x32_bf16 v[4:7], v[148:151], v[220:223], v[4:7]
	v_mfma_f32_16x16x32_bf16 v[0:3], v[156:159], v[220:223], v[0:3]
	v_mfma_f32_16x16x32_bf16 v[32:35], v[148:151], v[196:199], v[32:35]
	v_mfma_f32_16x16x32_bf16 v[36:39], v[156:159], v[196:199], v[36:39]
	v_mfma_f32_16x16x32_bf16 v[40:43], v[148:151], v[204:207], v[40:43]
	v_mfma_f32_16x16x32_bf16 v[44:47], v[156:159], v[204:207], v[44:47]
	s_setprio 0
	s_barrier
	s_add_i32 s49, 0, 0x18000
	s_add_i32 s51, 0, 0x1c000
	v_add_u32_e32 v68, s49, v183
	v_add_u32_e32 v156, s51, v183
	ds_read_b128 v[48:51], v68
	ds_read_b128 v[52:55], v68 offset:1024
	ds_read_b128 v[64:67], v68 offset:2048
	ds_read_b128 v[68:71], v68 offset:3072
	ds_read_b128 v[144:147], v156
	ds_read_b128 v[148:151], v156 offset:1024
	ds_read_b128 v[152:155], v156 offset:2048
	ds_read_b128 v[156:159], v156 offset:3072
	s_add_u32 s34, s56, 0x40000
	s_addc_u32 s35, s57, 0
	s_mov_b32 m0, s63
	v_lshl_add_u64 v[230:231], s[34:35], 0, v[160:161]
	ds_read_b128 v[192:195], v188 offset:32768
	ds_read_b128 v[196:199], v188 offset:33792
	ds_read_b128 v[200:203], v188 offset:34816
	ds_read_b128 v[204:207], v188 offset:35840
	ds_read_b128 v[208:211], v188 offset:36864
	ds_read_b128 v[212:215], v188 offset:37888
	ds_read_b128 v[216:219], v188 offset:38912
	ds_read_b128 v[220:223], v188 offset:39936
	global_load_lds_dwordx4 v[230:231], off
	v_lshl_add_u64 v[230:231], s[34:35], 0, v[164:165]
	s_mov_b32 m0, s64
	s_nop 0
	global_load_lds_dwordx4 v[230:231], off
	s_waitcnt vmcnt(8)
	s_waitcnt lgkmcnt(0)
	s_barrier
	s_setprio 1
	s_waitcnt lgkmcnt(0)
	v_mfma_f32_16x16x32_bf16 v[140:143], v[48:51], v[192:195], v[140:143]
	v_mfma_f32_16x16x32_bf16 v[136:139], v[64:67], v[192:195], v[136:139]
	v_mfma_f32_16x16x32_bf16 v[124:127], v[48:51], v[200:203], v[124:127]
	v_mfma_f32_16x16x32_bf16 v[120:123], v[64:67], v[200:203], v[120:123]
	v_mfma_f32_16x16x32_bf16 v[108:111], v[48:51], v[208:211], v[108:111]
	v_mfma_f32_16x16x32_bf16 v[104:107], v[64:67], v[208:211], v[104:107]
	v_mfma_f32_16x16x32_bf16 v[92:95], v[48:51], v[216:219], v[92:95]
	v_mfma_f32_16x16x32_bf16 v[88:91], v[64:67], v[216:219], v[88:91]
	v_mfma_f32_16x16x32_bf16 v[140:143], v[52:55], v[196:199], v[140:143]
	v_mfma_f32_16x16x32_bf16 v[136:139], v[68:71], v[196:199], v[136:139]
	v_mfma_f32_16x16x32_bf16 v[124:127], v[52:55], v[204:207], v[124:127]
	v_mfma_f32_16x16x32_bf16 v[120:123], v[68:71], v[204:207], v[120:123]
	v_mfma_f32_16x16x32_bf16 v[108:111], v[52:55], v[212:215], v[108:111]
	v_mfma_f32_16x16x32_bf16 v[104:107], v[68:71], v[212:215], v[104:107]
	v_mfma_f32_16x16x32_bf16 v[92:95], v[52:55], v[220:223], v[92:95]
	v_mfma_f32_16x16x32_bf16 v[88:91], v[68:71], v[220:223], v[88:91]
	s_setprio 0
	s_setprio 1
	v_mfma_f32_16x16x32_bf16 v[132:135], v[144:147], v[192:195], v[132:135]
	v_mfma_f32_16x16x32_bf16 v[128:131], v[152:155], v[192:195], v[128:131]
	v_mfma_f32_16x16x32_bf16 v[116:119], v[144:147], v[200:203], v[116:119]
	v_mfma_f32_16x16x32_bf16 v[112:115], v[152:155], v[200:203], v[112:115]
	v_mfma_f32_16x16x32_bf16 v[100:103], v[144:147], v[208:211], v[100:103]
	v_mfma_f32_16x16x32_bf16 v[96:99], v[152:155], v[208:211], v[96:99]
	v_mfma_f32_16x16x32_bf16 v[84:87], v[144:147], v[216:219], v[84:87]
	v_mfma_f32_16x16x32_bf16 v[80:83], v[152:155], v[216:219], v[80:83]
	v_mfma_f32_16x16x32_bf16 v[132:135], v[148:151], v[196:199], v[132:135]
	v_mfma_f32_16x16x32_bf16 v[128:131], v[156:159], v[196:199], v[128:131]
	v_mfma_f32_16x16x32_bf16 v[116:119], v[148:151], v[204:207], v[116:119]
	v_mfma_f32_16x16x32_bf16 v[112:115], v[156:159], v[204:207], v[112:115]
	v_mfma_f32_16x16x32_bf16 v[100:103], v[148:151], v[212:215], v[100:103]
	v_mfma_f32_16x16x32_bf16 v[96:99], v[156:159], v[212:215], v[96:99]
	v_mfma_f32_16x16x32_bf16 v[84:87], v[148:151], v[220:223], v[84:87]
	v_mfma_f32_16x16x32_bf16 v[80:83], v[156:159], v[220:223], v[80:83]
	s_setprio 0
	s_barrier
	s_add_i32 s34, s49, s60
	v_lshl_add_u64 v[180:181], v[180:181], 0, s[46:47]
	s_mov_b32 m0, s34
	ds_read_b128 v[192:195], v188 offset:49152
	ds_read_b128 v[196:199], v188 offset:50176
	ds_read_b128 v[200:203], v188 offset:51200
	ds_read_b128 v[204:207], v188 offset:52224
	ds_read_b128 v[208:211], v188 offset:53248
	ds_read_b128 v[212:215], v188 offset:54272
	ds_read_b128 v[216:219], v188 offset:55296
	ds_read_b128 v[220:223], v188 offset:56320
	global_load_lds_dwordx4 v[180:181], off
	s_add_i32 m0, s34, 0x2000
	s_add_u32 s8, s8, 0x40080
	v_lshl_add_u64 v[180:181], v[224:225], 0, s[46:47]
	s_addc_u32 s9, s9, 0
	s_add_i32 s34, s51, s60
	global_load_lds_dwordx4 v[180:181], off
	v_lshl_add_u64 v[180:181], s[8:9], 0, v[162:163]
	s_mov_b32 m0, s34
	s_nop 0
	global_load_lds_dwordx4 v[180:181], off
	v_lshl_add_u64 v[180:181], s[8:9], 0, v[166:167]
	s_add_i32 m0, s34, 0x2000
	s_nop 0
	global_load_lds_dwordx4 v[180:181], off
	v_lshl_add_u64 v[180:181], v[226:227], 0, s[46:47]
	s_mov_b32 m0, s78
	s_nop 0
	global_load_lds_dwordx4 v[180:181], off
	v_lshl_add_u64 v[180:181], v[228:229], 0, s[46:47]
	s_mov_b32 m0, s79
	s_nop 0
	global_load_lds_dwordx4 v[180:181], off
	s_waitcnt vmcnt(8)
	s_waitcnt lgkmcnt(0)
	s_barrier
	s_setprio 1
	s_waitcnt lgkmcnt(0)
	v_mfma_f32_16x16x32_bf16 v[76:79], v[48:51], v[192:195], v[76:79]
	v_mfma_f32_16x16x32_bf16 v[72:75], v[64:67], v[192:195], v[72:75]
	v_mfma_f32_16x16x32_bf16 v[60:63], v[48:51], v[200:203], v[60:63]
	v_mfma_f32_16x16x32_bf16 v[56:59], v[64:67], v[200:203], v[56:59]
	v_mfma_f32_16x16x32_bf16 v[28:31], v[48:51], v[208:211], v[28:31]
	v_mfma_f32_16x16x32_bf16 v[24:27], v[64:67], v[208:211], v[24:27]
	v_mfma_f32_16x16x32_bf16 v[12:15], v[48:51], v[216:219], v[12:15]
	v_mfma_f32_16x16x32_bf16 v[8:11], v[64:67], v[216:219], v[8:11]
	v_mfma_f32_16x16x32_bf16 v[76:79], v[52:55], v[196:199], v[76:79]
	v_mfma_f32_16x16x32_bf16 v[72:75], v[68:71], v[196:199], v[72:75]
	v_mfma_f32_16x16x32_bf16 v[60:63], v[52:55], v[204:207], v[60:63]
	v_mfma_f32_16x16x32_bf16 v[56:59], v[68:71], v[204:207], v[56:59]
	v_mfma_f32_16x16x32_bf16 v[28:31], v[52:55], v[212:215], v[28:31]
	v_mfma_f32_16x16x32_bf16 v[24:27], v[68:71], v[212:215], v[24:27]
	v_mfma_f32_16x16x32_bf16 v[12:15], v[52:55], v[220:223], v[12:15]
	v_mfma_f32_16x16x32_bf16 v[8:11], v[68:71], v[220:223], v[8:11]
	s_setprio 0
	s_setprio 1
	v_mfma_f32_16x16x32_bf16 v[32:35], v[144:147], v[192:195], v[32:35]
	v_mfma_f32_16x16x32_bf16 v[68:71], v[148:151], v[196:199], v[32:35]
	v_mfma_f32_16x16x32_bf16 v[32:35], v[152:155], v[192:195], v[36:39]
	v_mfma_f32_16x16x32_bf16 v[64:67], v[156:159], v[196:199], v[32:35]
	v_mfma_f32_16x16x32_bf16 v[32:35], v[144:147], v[200:203], v[40:43]
	v_mfma_f32_16x16x32_bf16 v[52:55], v[148:151], v[204:207], v[32:35]
	v_mfma_f32_16x16x32_bf16 v[32:35], v[152:155], v[200:203], v[44:47]
	v_mfma_f32_16x16x32_bf16 v[20:23], v[144:147], v[208:211], v[20:23]
	v_mfma_f32_16x16x32_bf16 v[16:19], v[152:155], v[208:211], v[16:19]
	v_mfma_f32_16x16x32_bf16 v[4:7], v[144:147], v[216:219], v[4:7]
	v_mfma_f32_16x16x32_bf16 v[0:3], v[152:155], v[216:219], v[0:3]
	v_mfma_f32_16x16x32_bf16 v[48:51], v[156:159], v[204:207], v[32:35]
	v_mfma_f32_16x16x32_bf16 v[20:23], v[148:151], v[212:215], v[20:23]
	v_mfma_f32_16x16x32_bf16 v[16:19], v[156:159], v[212:215], v[16:19]
	v_mfma_f32_16x16x32_bf16 v[4:7], v[148:151], v[220:223], v[4:7]
	v_mfma_f32_16x16x32_bf16 v[0:3], v[156:159], v[220:223], v[0:3]
	s_setprio 0
	s_barrier
	s_add_i32 s33, s33, 2
	s_add_u32 s6, s6, 0x100
	s_addc_u32 s7, s7, 0
	s_add_u32 s25, s25, 0x100
	s_addc_u32 s30, s30, 0
	s_cmp_gt_u32 s33, 13
	s_cbranch_scc0 .LBB5_625
	s_nop 0
	s_nop 0
	s_nop 0
	s_nop 0
	s_nop 0
	s_nop 0
	s_nop 0
	s_nop 0
	s_nop 0
	s_nop 0
	s_nop 0
	s_nop 0
	s_nop 0
	s_nop 0
	s_and_b64 vcc, exec, s[42:43]
	s_cbranch_vccz .LBB5_628
	s_barrier

.LBB5_969:
	ds_read_b128 v[128:131], v191
	ds_read_b128 v[132:135], v191 offset:1024
	ds_read_b128 v[136:139], v191 offset:2048
	ds_read_b128 v[140:143], v191 offset:3072
	ds_read_b128 v[144:147], v192
	ds_read_b128 v[148:151], v192 offset:1024
	ds_read_b128 v[168:171], v192 offset:2048
	ds_read_b128 v[172:175], v192 offset:3072
	s_add_u32 s40, s38, 0xfffc0080
	s_addc_u32 s41, s39, -1
	s_cmp_eq_u32 s57, 12
	s_cselect_b32 s43, s23, s41
	s_cselect_b32 s42, s37, s40
	s_cselect_b32 s41, s21, s56
	s_cselect_b32 s40, s54, s55
	v_lshl_add_u64 v[184:185], s[38:39], 0, v[160:161]
	s_add_i32 m0, s34, 0xc000
	ds_read_b128 v[176:179], v193
	ds_read_b128 v[180:183], v193 offset:1024
	ds_read_b128 v[194:197], v193 offset:2048
	ds_read_b128 v[198:201], v193 offset:3072
	ds_read_b128 v[202:205], v193 offset:4096
	ds_read_b128 v[206:209], v193 offset:5120
	ds_read_b128 v[210:213], v193 offset:6144
	ds_read_b128 v[214:217], v193 offset:7168
	global_load_lds_dwordx4 v[184:185], off
	v_lshl_add_u64 v[184:185], s[38:39], 0, v[162:163]
	s_add_i32 m0, s34, 0xe000
	s_nop 0
	global_load_lds_dwordx4 v[184:185], off
	s_cmp_eq_u32 s57, -2
	s_cbranch_scc1 .Lskw_P8
	s_waitcnt vmcnt(8)
.Lskw_P8:
	s_waitcnt lgkmcnt(0)
	s_barrier
	s_setprio 1
	s_waitcnt lgkmcnt(0)
	v_mfma_f32_16x16x32_bf16 v[124:127], v[128:131], v[176:179], v[124:127]
	v_mfma_f32_16x16x32_bf16 v[120:123], v[136:139], v[176:179], v[120:123]
	v_mfma_f32_16x16x32_bf16 v[108:111], v[128:131], v[194:197], v[108:111]
	v_mfma_f32_16x16x32_bf16 v[104:107], v[136:139], v[194:197], v[104:107]
	v_mfma_f32_16x16x32_bf16 v[92:95], v[128:131], v[202:205], v[92:95]
	v_mfma_f32_16x16x32_bf16 v[88:91], v[136:139], v[202:205], v[88:91]
	v_mfma_f32_16x16x32_bf16 v[76:79], v[128:131], v[210:213], v[76:79]
	v_mfma_f32_16x16x32_bf16 v[72:75], v[136:139], v[210:213], v[72:75]
	v_mfma_f32_16x16x32_bf16 v[124:127], v[132:135], v[180:183], v[124:127]
	v_mfma_f32_16x16x32_bf16 v[120:123], v[140:143], v[180:183], v[120:123]
	v_mfma_f32_16x16x32_bf16 v[108:111], v[132:135], v[198:201], v[108:111]
	v_mfma_f32_16x16x32_bf16 v[104:107], v[140:143], v[198:201], v[104:107]
	v_mfma_f32_16x16x32_bf16 v[92:95], v[132:135], v[206:209], v[92:95]
	v_mfma_f32_16x16x32_bf16 v[88:91], v[140:143], v[206:209], v[88:91]
	v_mfma_f32_16x16x32_bf16 v[76:79], v[132:135], v[214:217], v[76:79]
	v_mfma_f32_16x16x32_bf16 v[72:75], v[140:143], v[214:217], v[72:75]
	s_setprio 0
	s_setprio 1
	v_mfma_f32_16x16x32_bf16 v[116:119], v[144:147], v[176:179], v[116:119]
	v_mfma_f32_16x16x32_bf16 v[112:115], v[168:171], v[176:179], v[112:115]
	v_mfma_f32_16x16x32_bf16 v[100:103], v[144:147], v[194:197], v[100:103]
	v_mfma_f32_16x16x32_bf16 v[96:99], v[168:171], v[194:197], v[96:99]
	v_mfma_f32_16x16x32_bf16 v[84:87], v[144:147], v[202:205], v[84:87]
	v_mfma_f32_16x16x32_bf16 v[80:83], v[168:171], v[202:205], v[80:83]
	v_mfma_f32_16x16x32_bf16 v[68:71], v[144:147], v[210:213], v[68:71]
	v_mfma_f32_16x16x32_bf16 v[64:67], v[168:171], v[210:213], v[64:67]
	v_mfma_f32_16x16x32_bf16 v[116:119], v[148:151], v[180:183], v[116:119]
	v_mfma_f32_16x16x32_bf16 v[112:115], v[172:175], v[180:183], v[112:115]
	v_mfma_f32_16x16x32_bf16 v[100:103], v[148:151], v[198:201], v[100:103]
	v_mfma_f32_16x16x32_bf16 v[96:99], v[172:175], v[198:201], v[96:99]
	v_mfma_f32_16x16x32_bf16 v[84:87], v[148:151], v[206:209], v[84:87]
	v_mfma_f32_16x16x32_bf16 v[80:83], v[172:175], v[206:209], v[80:83]
	v_mfma_f32_16x16x32_bf16 v[68:71], v[148:151], v[214:217], v[68:71]
	v_mfma_f32_16x16x32_bf16 v[64:67], v[172:175], v[214:217], v[64:67]
	s_setprio 0
	s_barrier
	s_add_i32 s58, s51, s33
	v_lshl_add_u64 v[184:185], s[40:41], 0, v[154:155]
	s_mov_b32 m0, s58
	ds_read_b128 v[176:179], v193 offset:16384
	ds_read_b128 v[180:183], v193 offset:17408
	ds_read_b128 v[194:197], v193 offset:18432
	ds_read_b128 v[198:201], v193 offset:19456
	ds_read_b128 v[202:205], v193 offset:20480
	ds_read_b128 v[206:209], v193 offset:21504
	ds_read_b128 v[210:213], v193 offset:22528
	ds_read_b128 v[214:217], v193 offset:23552
	global_load_lds_dwordx4 v[184:185], off
	s_add_i32 m0, s58, 0x2000
	s_add_u32 s58, s40, 0x40000
	v_lshl_add_u64 v[218:219], s[40:41], 0, v[158:159]
	s_addc_u32 s59, s41, 0
	s_add_i32 s60, s52, s33
	global_load_lds_dwordx4 v[218:219], off
	v_lshl_add_u64 v[220:221], s[58:59], 0, v[154:155]
	s_mov_b32 m0, s60
	v_lshl_add_u64 v[222:223], s[42:43], 0, v[156:157]
	global_load_lds_dwordx4 v[220:221], off
	v_lshl_add_u64 v[220:221], s[58:59], 0, v[158:159]
	s_add_i32 m0, s60, 0x2000
	s_nop 0
	global_load_lds_dwordx4 v[220:221], off
	v_lshl_add_u64 v[220:221], s[42:43], 0, v[152:153]
	s_mov_b32 m0, s34
	s_nop 0
	global_load_lds_dwordx4 v[220:221], off
	s_mov_b32 m0, s35
	s_nop 0
	global_load_lds_dwordx4 v[222:223], off
	s_waitcnt vmcnt(8)
	s_waitcnt lgkmcnt(0)
	s_barrier
	s_setprio 1
	s_waitcnt lgkmcnt(0)
	v_mfma_f32_16x16x32_bf16 v[60:63], v[128:131], v[176:179], v[60:63]
	v_mfma_f32_16x16x32_bf16 v[56:59], v[136:139], v[176:179], v[56:59]
	v_mfma_f32_16x16x32_bf16 v[44:47], v[128:131], v[194:197], v[44:47]
	v_mfma_f32_16x16x32_bf16 v[40:43], v[136:139], v[194:197], v[40:43]
	v_mfma_f32_16x16x32_bf16 v[28:31], v[128:131], v[202:205], v[28:31]
	v_mfma_f32_16x16x32_bf16 v[24:27], v[136:139], v[202:205], v[24:27]
	v_mfma_f32_16x16x32_bf16 v[12:15], v[128:131], v[210:213], v[12:15]
	v_mfma_f32_16x16x32_bf16 v[8:11], v[136:139], v[210:213], v[8:11]
	v_mfma_f32_16x16x32_bf16 v[60:63], v[132:135], v[180:183], v[60:63]
	v_mfma_f32_16x16x32_bf16 v[56:59], v[140:143], v[180:183], v[56:59]
	v_mfma_f32_16x16x32_bf16 v[44:47], v[132:135], v[198:201], v[44:47]
	v_mfma_f32_16x16x32_bf16 v[40:43], v[140:143], v[198:201], v[40:43]
	v_mfma_f32_16x16x32_bf16 v[28:31], v[132:135], v[206:209], v[28:31]
	v_mfma_f32_16x16x32_bf16 v[24:27], v[140:143], v[206:209], v[24:27]
	v_mfma_f32_16x16x32_bf16 v[12:15], v[132:135], v[214:217], v[12:15]
	v_mfma_f32_16x16x32_bf16 v[8:11], v[140:143], v[214:217], v[8:11]
	s_setprio 0
	s_setprio 1
	v_mfma_f32_16x16x32_bf16 v[52:55], v[144:147], v[176:179], v[52:55]
	v_mfma_f32_16x16x32_bf16 v[48:51], v[168:171], v[176:179], v[48:51]
	v_mfma_f32_16x16x32_bf16 v[36:39], v[144:147], v[194:197], v[36:39]
	v_mfma_f32_16x16x32_bf16 v[32:35], v[168:171], v[194:197], v[32:35]
	v_mfma_f32_16x16x32_bf16 v[20:23], v[144:147], v[202:205], v[20:23]
	v_mfma_f32_16x16x32_bf16 v[16:19], v[168:171], v[202:205], v[16:19]
	v_mfma_f32_16x16x32_bf16 v[4:7], v[144:147], v[210:213], v[4:7]
	v_mfma_f32_16x16x32_bf16 v[0:3], v[168:171], v[210:213], v[0:3]
	v_mfma_f32_16x16x32_bf16 v[52:55], v[148:151], v[180:183], v[52:55]
	v_mfma_f32_16x16x32_bf16 v[48:51], v[172:175], v[180:183], v[48:51]
	v_mfma_f32_16x16x32_bf16 v[36:39], v[148:151], v[198:201], v[36:39]
	v_mfma_f32_16x16x32_bf16 v[32:35], v[172:175], v[198:201], v[32:35]
	v_mfma_f32_16x16x32_bf16 v[20:23], v[148:151], v[206:209], v[20:23]
	v_mfma_f32_16x16x32_bf16 v[16:19], v[172:175], v[206:209], v[16:19]
	v_mfma_f32_16x16x32_bf16 v[4:7], v[148:151], v[214:217], v[4:7]
	v_mfma_f32_16x16x32_bf16 v[0:3], v[172:175], v[214:217], v[0:3]
	s_setprio 0
	s_barrier
	s_add_i32 s58, 0, 0x18000
	s_add_i32 s59, 0, 0x1c000
	v_add_u32_e32 v140, s58, v187
	v_add_u32_e32 v172, s59, v187
	ds_read_b128 v[128:131], v140
	ds_read_b128 v[132:135], v140 offset:1024
	ds_read_b128 v[136:139], v140 offset:2048
	ds_read_b128 v[140:143], v140 offset:3072
	ds_read_b128 v[144:147], v172
	ds_read_b128 v[148:151], v172 offset:1024
	ds_read_b128 v[168:171], v172 offset:2048
	ds_read_b128 v[172:175], v172 offset:3072
	s_add_u32 s42, s42, 0x40000
	s_addc_u32 s43, s43, 0
	s_mov_b32 m0, s44
	v_lshl_add_u64 v[224:225], s[42:43], 0, v[152:153]
	ds_read_b128 v[176:179], v193 offset:32768
	ds_read_b128 v[180:183], v193 offset:33792
	ds_read_b128 v[194:197], v193 offset:34816
	ds_read_b128 v[198:201], v193 offset:35840
	ds_read_b128 v[202:205], v193 offset:36864
	ds_read_b128 v[206:209], v193 offset:37888
	ds_read_b128 v[210:213], v193 offset:38912
	ds_read_b128 v[214:217], v193 offset:39936
	global_load_lds_dwordx4 v[224:225], off
	v_lshl_add_u64 v[224:225], s[42:43], 0, v[156:157]
	s_mov_b32 m0, s45
	s_nop 0
	global_load_lds_dwordx4 v[224:225], off
	s_waitcnt vmcnt(8)
	s_waitcnt lgkmcnt(0)
	s_barrier
	s_setprio 1
	s_waitcnt lgkmcnt(0)
	v_mfma_f32_16x16x32_bf16 v[124:127], v[128:131], v[176:179], v[124:127]
	v_mfma_f32_16x16x32_bf16 v[120:123], v[136:139], v[176:179], v[120:123]
	v_mfma_f32_16x16x32_bf16 v[108:111], v[128:131], v[194:197], v[108:111]
	v_mfma_f32_16x16x32_bf16 v[104:107], v[136:139], v[194:197], v[104:107]
	v_mfma_f32_16x16x32_bf16 v[92:95], v[128:131], v[202:205], v[92:95]
	v_mfma_f32_16x16x32_bf16 v[88:91], v[136:139], v[202:205], v[88:91]
	v_mfma_f32_16x16x32_bf16 v[76:79], v[128:131], v[210:213], v[76:79]
	v_mfma_f32_16x16x32_bf16 v[72:75], v[136:139], v[210:213], v[72:75]
	v_mfma_f32_16x16x32_bf16 v[124:127], v[132:135], v[180:183], v[124:127]
	v_mfma_f32_16x16x32_bf16 v[120:123], v[140:143], v[180:183], v[120:123]
	v_mfma_f32_16x16x32_bf16 v[108:111], v[132:135], v[198:201], v[108:111]
	v_mfma_f32_16x16x32_bf16 v[104:107], v[140:143], v[198:201], v[104:107]
	v_mfma_f32_16x16x32_bf16 v[92:95], v[132:135], v[206:209], v[92:95]
	v_mfma_f32_16x16x32_bf16 v[88:91], v[140:143], v[206:209], v[88:91]
	v_mfma_f32_16x16x32_bf16 v[76:79], v[132:135], v[214:217], v[76:79]
	v_mfma_f32_16x16x32_bf16 v[72:75], v[140:143], v[214:217], v[72:75]
	s_setprio 0
	s_setprio 1
	v_mfma_f32_16x16x32_bf16 v[116:119], v[144:147], v[176:179], v[116:119]
	v_mfma_f32_16x16x32_bf16 v[112:115], v[168:171], v[176:179], v[112:115]
	v_mfma_f32_16x16x32_bf16 v[100:103], v[144:147], v[194:197], v[100:103]
	v_mfma_f32_16x16x32_bf16 v[96:99], v[168:171], v[194:197], v[96:99]
	v_mfma_f32_16x16x32_bf16 v[84:87], v[144:147], v[202:205], v[84:87]
	v_mfma_f32_16x16x32_bf16 v[80:83], v[168:171], v[202:205], v[80:83]
	v_mfma_f32_16x16x32_bf16 v[68:71], v[144:147], v[210:213], v[68:71]
	v_mfma_f32_16x16x32_bf16 v[64:67], v[168:171], v[210:213], v[64:67]
	v_mfma_f32_16x16x32_bf16 v[116:119], v[148:151], v[180:183], v[116:119]
	v_mfma_f32_16x16x32_bf16 v[112:115], v[172:175], v[180:183], v[112:115]
	v_mfma_f32_16x16x32_bf16 v[100:103], v[148:151], v[198:201], v[100:103]
	v_mfma_f32_16x16x32_bf16 v[96:99], v[172:175], v[198:201], v[96:99]
	v_mfma_f32_16x16x32_bf16 v[84:87], v[148:151], v[206:209], v[84:87]
	v_mfma_f32_16x16x32_bf16 v[80:83], v[172:175], v[206:209], v[80:83]
	v_mfma_f32_16x16x32_bf16 v[68:71], v[148:151], v[214:217], v[68:71]
	v_mfma_f32_16x16x32_bf16 v[64:67], v[172:175], v[214:217], v[64:67]
	s_setprio 0
	s_barrier
	s_add_i32 s42, s58, s33
	v_lshl_add_u64 v[184:185], v[184:185], 0, s[18:19]
	s_mov_b32 m0, s42
	ds_read_b128 v[176:179], v193 offset:49152
	ds_read_b128 v[180:183], v193 offset:50176
	ds_read_b128 v[194:197], v193 offset:51200
	ds_read_b128 v[198:201], v193 offset:52224
	ds_read_b128 v[202:205], v193 offset:53248
	ds_read_b128 v[206:209], v193 offset:54272
	ds_read_b128 v[210:213], v193 offset:55296
	ds_read_b128 v[214:217], v193 offset:56320
	global_load_lds_dwordx4 v[184:185], off
	s_add_i32 m0, s42, 0x2000
	s_add_u32 s40, s40, 0x40080
	v_lshl_add_u64 v[184:185], v[218:219], 0, s[18:19]
	s_addc_u32 s41, s41, 0
	s_add_i32 s42, s59, s33
	global_load_lds_dwordx4 v[184:185], off
	v_lshl_add_u64 v[184:185], s[40:41], 0, v[154:155]
	s_mov_b32 m0, s42
	s_nop 0
	global_load_lds_dwordx4 v[184:185], off
	v_lshl_add_u64 v[184:185], s[40:41], 0, v[158:159]
	s_add_i32 m0, s42, 0x2000
	s_nop 0
	global_load_lds_dwordx4 v[184:185], off
	v_lshl_add_u64 v[184:185], v[220:221], 0, s[18:19]
	s_mov_b32 m0, s49
	s_nop 0
	global_load_lds_dwordx4 v[184:185], off
	v_lshl_add_u64 v[184:185], v[222:223], 0, s[18:19]
	s_mov_b32 m0, s50
	s_nop 0
	global_load_lds_dwordx4 v[184:185], off
	s_waitcnt vmcnt(8)
	s_waitcnt lgkmcnt(0)
	s_barrier
	s_setprio 1
	s_waitcnt lgkmcnt(0)
	v_mfma_f32_16x16x32_bf16 v[60:63], v[128:131], v[176:179], v[60:63]
	v_mfma_f32_16x16x32_bf16 v[56:59], v[136:139], v[176:179], v[56:59]
	v_mfma_f32_16x16x32_bf16 v[44:47], v[128:131], v[194:197], v[44:47]
	v_mfma_f32_16x16x32_bf16 v[40:43], v[136:139], v[194:197], v[40:43]
	v_mfma_f32_16x16x32_bf16 v[28:31], v[128:131], v[202:205], v[28:31]
	v_mfma_f32_16x16x32_bf16 v[24:27], v[136:139], v[202:205], v[24:27]
	v_mfma_f32_16x16x32_bf16 v[12:15], v[128:131], v[210:213], v[12:15]
	v_mfma_f32_16x16x32_bf16 v[8:11], v[136:139], v[210:213], v[8:11]
	v_mfma_f32_16x16x32_bf16 v[60:63], v[132:135], v[180:183], v[60:63]
	v_mfma_f32_16x16x32_bf16 v[56:59], v[140:143], v[180:183], v[56:59]
	v_mfma_f32_16x16x32_bf16 v[44:47], v[132:135], v[198:201], v[44:47]
	v_mfma_f32_16x16x32_bf16 v[40:43], v[140:143], v[198:201], v[40:43]
	v_mfma_f32_16x16x32_bf16 v[28:31], v[132:135], v[206:209], v[28:31]
	v_mfma_f32_16x16x32_bf16 v[24:27], v[140:143], v[206:209], v[24:27]
	v_mfma_f32_16x16x32_bf16 v[12:15], v[132:135], v[214:217], v[12:15]
	v_mfma_f32_16x16x32_bf16 v[8:11], v[140:143], v[214:217], v[8:11]
	s_setprio 0
	s_setprio 1
	v_mfma_f32_16x16x32_bf16 v[52:55], v[144:147], v[176:179], v[52:55]
	v_mfma_f32_16x16x32_bf16 v[48:51], v[168:171], v[176:179], v[48:51]
	v_mfma_f32_16x16x32_bf16 v[36:39], v[144:147], v[194:197], v[36:39]
	v_mfma_f32_16x16x32_bf16 v[32:35], v[168:171], v[194:197], v[32:35]
	v_mfma_f32_16x16x32_bf16 v[20:23], v[144:147], v[202:205], v[20:23]
	v_mfma_f32_16x16x32_bf16 v[16:19], v[168:171], v[202:205], v[16:19]
	v_mfma_f32_16x16x32_bf16 v[4:7], v[144:147], v[210:213], v[4:7]
	v_mfma_f32_16x16x32_bf16 v[0:3], v[168:171], v[210:213], v[0:3]
	v_mfma_f32_16x16x32_bf16 v[52:55], v[148:151], v[180:183], v[52:55]
	v_mfma_f32_16x16x32_bf16 v[48:51], v[172:175], v[180:183], v[48:51]
	v_mfma_f32_16x16x32_bf16 v[36:39], v[148:151], v[198:201], v[36:39]
	v_mfma_f32_16x16x32_bf16 v[32:35], v[172:175], v[198:201], v[32:35]
	v_mfma_f32_16x16x32_bf16 v[20:23], v[148:151], v[206:209], v[20:23]
	v_mfma_f32_16x16x32_bf16 v[16:19], v[172:175], v[206:209], v[16:19]
	v_mfma_f32_16x16x32_bf16 v[4:7], v[148:151], v[214:217], v[4:7]
	v_mfma_f32_16x16x32_bf16 v[0:3], v[172:175], v[214:217], v[0:3]
	s_setprio 0
	s_barrier
	s_add_i32 s57, s57, 2
	s_add_u32 s38, s38, 0x100
	s_addc_u32 s39, s39, 0
	s_add_u32 s55, s55, 0x100
	s_addc_u32 s56, s56, 0
	s_cmp_gt_u32 s57, 13
	s_cbranch_scc0 .LBB5_969
	s_nop 0
	s_nop 0
	s_nop 0
	s_nop 0
	s_nop 0
	s_nop 0
	s_nop 0
	s_nop 0
	s_nop 0
	s_nop 0
	s_nop 0
	s_nop 0
	s_nop 0
	s_nop 0
	s_and_b64 vcc, exec, s[16:17]
	s_cbranch_vccz .LBB5_972
	s_barrier
